# MFMA order: k-steps of an accumulator back to back, accumulators visited in snake order with alternating k direction so each switch keeps one of A/B
# baseline (speedup 1.0000x reference)
; #define PG8_STAGE(bufoff, gbase, voff) do { _Pragma("unroll") for (int _i = 0; _i < 2; ++_i) \
;         __builtin_amdgcn_global_load_lds((const unsigned*)((const char*)(gbase) + (voff)[_i]), (PG8_LAS unsigned*)(lds + (bufoff) + ldsw + _i * 8192), 16, 0, 0); } while (0)
; #define PG8_LDA(dst, b, h) do { _Pragma("unroll") for (int m = 0; m < 4; ++m) _Pragma("unroll") for (int k = 0; k < 2; ++k) dst[m][k] = *(const PG8_LAS bf16x8*)(lds + PG8_SA(b, h) + aoff + m * 2048 + k * 1024); } while (0)
; #define PG8_LDB(dst, b, h) do { _Pragma("unroll") for (int n = 0; n < 2; ++n) _Pragma("unroll") for (int k = 0; k < 2; ++k) dst[n][k] = *(const PG8_LAS bf16x8*)(lds + PG8_SB(b, h) + boff + n * 2048 + k * 1024); } while (0)
; #define PG8_MMA(ai, bj, At, Bt) do { __builtin_amdgcn_s_setprio(1); _Pragma("unroll") for (int m = 0; m < 4; ++m) _Pragma("unroll") for (int n = 0; n < 2; ++n) _Pragma("unroll") for (int k = 0; k < 2; ++k) \
;         acc[ai][bj][m][n] = __builtin_amdgcn_mfma_f32_16x16x32_bf16(Bt[n][k], At[m][k], acc[ai][bj][m][n], 0, 0, 0); __builtin_amdgcn_s_setprio(0); } while (0)
; #define PG8_WAIT_V(n) asm volatile("s_waitcnt vmcnt(" #n ")" ::: "memory")
; #define PG8_WAIT_L(n) asm volatile("s_waitcnt lgkmcnt(" #n ")" ::: "memory")
; #define PG8_BAR __builtin_amdgcn_s_barrier()
; #define PG8_SCHED __builtin_amdgcn_sched_barrier(0)
; template <class Epi, class Sched, bool ALIGN_EPI = false, bool SP2 = false>
; __device__ __forceinline__ void gemm_phase(PG8_LAS unsigned char* lds, const Gemm g, const Sched& S, const Epi& E) {
;     ...
;             PG8_LDB(B0, 0, 0); PG8_LDB(B1, 0, 1); PG8_SCHED; PG8_LDA(At, 0, 0); PG8_STAGE(PG8_SA(1, 1), a1 + hstep, voffA);
;             PG8_WAIT_V(8); PG8_WAIT_L(0); PG8_BAR; PG8_MMA(0, 0, At, B0); PG8_MMA(0, 1, At, B1); PG8_BAR; PG8_SCHED;
;             PG8_LDA(At, 0, 1); PG8_STAGE(PG8_SB(0, 0), b2, voffB); PG8_STAGE(PG8_SB(0, 1), b2 + hstepB, voffB); PG8_STAGE(PG8_SA(0, 0), a2, voffA);
;             PG8_WAIT_V(8); PG8_WAIT_L(0); PG8_BAR; PG8_MMA(1, 0, At, B0); PG8_MMA(1, 1, At, B1); PG8_BAR; PG8_SCHED;
.LBB0_402:
	ds_read_b128 v[82:85], v178
	ds_read_b128 v[86:89], v178 offset:1024
	ds_read_b128 v[90:93], v178 offset:2048
	ds_read_b128 v[94:97], v178 offset:3072
	ds_read_b128 v[186:189], v179
	ds_read_b128 v[190:193], v179 offset:1024
	ds_read_b128 v[194:197], v179 offset:2048
	ds_read_b128 v[198:201], v179 offset:3072
	s_add_u32 s10, s6, 0xfff00080
	s_addc_u32 s11, s7, -1
	s_cmp_eq_u32 s51, 60
	s_cselect_b32 s35, s23, s11
	s_cselect_b32 s34, s47, s10
	s_cselect_b32 s11, s21, s50
	s_cselect_b32 s10, s48, s49
	v_lshl_add_u64 v[234:235], s[6:7], 0, v[158:159]
	s_add_i32 m0, s29, 0xc000
	ds_read_b128 v[202:205], v180
	ds_read_b128 v[206:209], v180 offset:1024
	ds_read_b128 v[210:213], v180 offset:2048
	ds_read_b128 v[214:217], v180 offset:3072
	ds_read_b128 v[218:221], v180 offset:4096
	ds_read_b128 v[222:225], v180 offset:5120
	ds_read_b128 v[226:229], v180 offset:6144
	ds_read_b128 v[230:233], v180 offset:7168
	global_load_lds_dwordx4 v[234:235], off
	v_lshl_add_u64 v[234:235], s[6:7], 0, v[160:161]
	s_add_i32 m0, s29, 0xe000
	s_nop 0
	global_load_lds_dwordx4 v[234:235], off
	s_waitcnt vmcnt(8)
	s_waitcnt lgkmcnt(0)
	s_barrier
	s_setprio 1
	s_waitcnt lgkmcnt(0)
	v_mfma_f32_16x16x32_bf16 v[142:145], v[82:85], v[202:205], v[142:145]
	v_mfma_f32_16x16x32_bf16 v[142:145], v[86:89], v[206:209], v[142:145]
	v_mfma_f32_16x16x32_bf16 v[138:141], v[94:97], v[206:209], v[138:141]
	v_mfma_f32_16x16x32_bf16 v[138:141], v[90:93], v[202:205], v[138:141]
	v_mfma_f32_16x16x32_bf16 v[122:125], v[90:93], v[210:213], v[122:125]
	v_mfma_f32_16x16x32_bf16 v[122:125], v[94:97], v[214:217], v[122:125]
	v_mfma_f32_16x16x32_bf16 v[126:129], v[86:89], v[214:217], v[126:129]
	v_mfma_f32_16x16x32_bf16 v[126:129], v[82:85], v[210:213], v[126:129]
	v_mfma_f32_16x16x32_bf16 v[110:113], v[82:85], v[218:221], v[110:113]
	v_mfma_f32_16x16x32_bf16 v[110:113], v[86:89], v[222:225], v[110:113]
	v_mfma_f32_16x16x32_bf16 v[106:109], v[94:97], v[222:225], v[106:109]
	v_mfma_f32_16x16x32_bf16 v[106:109], v[90:93], v[218:221], v[106:109]
	v_mfma_f32_16x16x32_bf16 v[74:77], v[90:93], v[226:229], v[74:77]
	v_mfma_f32_16x16x32_bf16 v[74:77], v[94:97], v[230:233], v[74:77]
	v_mfma_f32_16x16x32_bf16 v[78:81], v[86:89], v[230:233], v[78:81]
	v_mfma_f32_16x16x32_bf16 v[78:81], v[82:85], v[226:229], v[78:81]
	s_setprio 0
	s_setprio 1
	v_mfma_f32_16x16x32_bf16 v[134:137], v[186:189], v[202:205], v[134:137]
	v_mfma_f32_16x16x32_bf16 v[134:137], v[190:193], v[206:209], v[134:137]
	v_mfma_f32_16x16x32_bf16 v[130:133], v[198:201], v[206:209], v[130:133]
	v_mfma_f32_16x16x32_bf16 v[130:133], v[194:197], v[202:205], v[130:133]
	v_mfma_f32_16x16x32_bf16 v[114:117], v[194:197], v[210:213], v[114:117]
	v_mfma_f32_16x16x32_bf16 v[114:117], v[198:201], v[214:217], v[114:117]
	v_mfma_f32_16x16x32_bf16 v[118:121], v[190:193], v[214:217], v[118:121]
	v_mfma_f32_16x16x32_bf16 v[118:121], v[186:189], v[210:213], v[118:121]
	v_mfma_f32_16x16x32_bf16 v[102:105], v[186:189], v[218:221], v[102:105]
	v_mfma_f32_16x16x32_bf16 v[102:105], v[190:193], v[222:225], v[102:105]
	v_mfma_f32_16x16x32_bf16 v[98:101], v[198:201], v[222:225], v[98:101]
	v_mfma_f32_16x16x32_bf16 v[98:101], v[194:197], v[218:221], v[98:101]
	v_mfma_f32_16x16x32_bf16 v[66:69], v[194:197], v[226:229], v[66:69]
	v_mfma_f32_16x16x32_bf16 v[66:69], v[198:201], v[230:233], v[66:69]
	v_mfma_f32_16x16x32_bf16 v[70:73], v[190:193], v[230:233], v[70:73]
	v_mfma_f32_16x16x32_bf16 v[70:73], v[186:189], v[226:229], v[70:73]
	s_setprio 0
	s_barrier
	s_add_i32 s52, s42, s37
	v_lshl_add_u64 v[234:235], s[10:11], 0, v[148:149]
	s_mov_b32 m0, s52
	ds_read_b128 v[202:205], v180 offset:16384
	ds_read_b128 v[206:209], v180 offset:17408
	ds_read_b128 v[210:213], v180 offset:18432
	ds_read_b128 v[214:217], v180 offset:19456
	ds_read_b128 v[218:221], v180 offset:20480
	ds_read_b128 v[222:225], v180 offset:21504
	ds_read_b128 v[226:229], v180 offset:22528
	ds_read_b128 v[230:233], v180 offset:23552
	global_load_lds_dwordx4 v[234:235], off
	s_add_i32 m0, s52, 0x2000
	s_add_u32 s52, s10, 0x40000
	v_lshl_add_u64 v[236:237], s[10:11], 0, v[152:153]
	s_addc_u32 s53, s11, 0
	s_add_i32 s54, s43, s37
	global_load_lds_dwordx4 v[236:237], off
	v_lshl_add_u64 v[238:239], s[52:53], 0, v[148:149]
	s_mov_b32 m0, s54
	v_lshl_add_u64 v[240:241], s[34:35], 0, v[150:151]
	global_load_lds_dwordx4 v[238:239], off
	v_lshl_add_u64 v[238:239], s[52:53], 0, v[152:153]
	s_add_i32 m0, s54, 0x2000
	s_nop 0
	global_load_lds_dwordx4 v[238:239], off
	v_lshl_add_u64 v[238:239], s[34:35], 0, v[146:147]
	s_mov_b32 m0, s29
	s_nop 0
	global_load_lds_dwordx4 v[238:239], off
	s_mov_b32 m0, s31
	s_nop 0
	global_load_lds_dwordx4 v[240:241], off
	s_waitcnt vmcnt(8)
	s_waitcnt lgkmcnt(0)
	s_barrier
; #define PG8_STAGE(bufoff, gbase, voff) do { _Pragma("unroll") for (int _i = 0; _i < 2; ++_i) \
;         __builtin_amdgcn_global_load_lds((const unsigned*)((const char*)(gbase) + (voff)[_i]), (PG8_LAS unsigned*)(lds + (bufoff) + ldsw + _i * 8192), 16, 0, 0); } while (0)
; #define PG8_LDA(dst, b, h) do { _Pragma("unroll") for (int m = 0; m < 4; ++m) _Pragma("unroll") for (int k = 0; k < 2; ++k) dst[m][k] = *(const PG8_LAS bf16x8*)(lds + PG8_SA(b, h) + aoff + m * 2048 + k * 1024); } while (0)
; #define PG8_LDB(dst, b, h) do { _Pragma("unroll") for (int n = 0; n < 2; ++n) _Pragma("unroll") for (int k = 0; k < 2; ++k) dst[n][k] = *(const PG8_LAS bf16x8*)(lds + PG8_SB(b, h) + boff + n * 2048 + k * 1024); } while (0)
; #define PG8_MMA(ai, bj, At, Bt) do { __builtin_amdgcn_s_setprio(1); _Pragma("unroll") for (int m = 0; m < 4; ++m) _Pragma("unroll") for (int n = 0; n < 2; ++n) _Pragma("unroll") for (int k = 0; k < 2; ++k) \
;         acc[ai][bj][m][n] = __builtin_amdgcn_mfma_f32_16x16x32_bf16(Bt[n][k], At[m][k], acc[ai][bj][m][n], 0, 0, 0); __builtin_amdgcn_s_setprio(0); } while (0)
; #define PG8_WAIT_V(n) asm volatile("s_waitcnt vmcnt(" #n ")" ::: "memory")
; #define PG8_WAIT_L(n) asm volatile("s_waitcnt lgkmcnt(" #n ")" ::: "memory")
; #define PG8_BAR __builtin_amdgcn_s_barrier()
; #define PG8_SCHED __builtin_amdgcn_sched_barrier(0)
; template <class Epi, class Sched, bool ALIGN_EPI = false, bool SP2 = false>
; __device__ __forceinline__ void gemm_phase(PG8_LAS unsigned char* lds, const Gemm g, const Sched& S, const Epi& E) {
;     ...
;             PG8_WAIT_V(8); PG8_WAIT_L(0); PG8_BAR; PG8_MMA(1, 0, At, B0); PG8_MMA(1, 1, At, B1); PG8_BAR; PG8_SCHED;
;             PG8_LDB(B0, 1, 0); PG8_LDB(B1, 1, 1); PG8_SCHED; PG8_LDA(At, 1, 0); PG8_STAGE(PG8_SA(0, 1), a2 + hstep, voffA);
;             PG8_WAIT_V(8); PG8_WAIT_L(0); PG8_BAR; PG8_MMA(0, 0, At, B0); PG8_MMA(0, 1, At, B1); PG8_BAR; PG8_SCHED;
	s_setprio 1
	s_waitcnt lgkmcnt(0)
	v_mfma_f32_16x16x32_bf16 v[62:65], v[82:85], v[202:205], v[62:65]
	v_mfma_f32_16x16x32_bf16 v[62:65], v[86:89], v[206:209], v[62:65]
	v_mfma_f32_16x16x32_bf16 v[58:61], v[94:97], v[206:209], v[58:61]
	v_mfma_f32_16x16x32_bf16 v[58:61], v[90:93], v[202:205], v[58:61]
	v_mfma_f32_16x16x32_bf16 v[42:45], v[90:93], v[210:213], v[42:45]
	v_mfma_f32_16x16x32_bf16 v[42:45], v[94:97], v[214:217], v[42:45]
	v_mfma_f32_16x16x32_bf16 v[46:49], v[86:89], v[214:217], v[46:49]
	v_mfma_f32_16x16x32_bf16 v[46:49], v[82:85], v[210:213], v[46:49]
	v_mfma_f32_16x16x32_bf16 v[30:33], v[82:85], v[218:221], v[30:33]
	v_mfma_f32_16x16x32_bf16 v[30:33], v[86:89], v[222:225], v[30:33]
	v_mfma_f32_16x16x32_bf16 v[26:29], v[94:97], v[222:225], v[26:29]
	v_mfma_f32_16x16x32_bf16 v[26:29], v[90:93], v[218:221], v[26:29]
	v_mfma_f32_16x16x32_bf16 v[10:13], v[90:93], v[226:229], v[10:13]
	v_mfma_f32_16x16x32_bf16 v[10:13], v[94:97], v[230:233], v[10:13]
	v_mfma_f32_16x16x32_bf16 v[14:17], v[86:89], v[230:233], v[14:17]
	v_mfma_f32_16x16x32_bf16 v[14:17], v[82:85], v[226:229], v[14:17]
	s_setprio 0
	s_setprio 1
	v_mfma_f32_16x16x32_bf16 v[54:57], v[186:189], v[202:205], v[54:57]
	v_mfma_f32_16x16x32_bf16 v[54:57], v[190:193], v[206:209], v[54:57]
	v_mfma_f32_16x16x32_bf16 v[50:53], v[198:201], v[206:209], v[50:53]
	v_mfma_f32_16x16x32_bf16 v[50:53], v[194:197], v[202:205], v[50:53]
	v_mfma_f32_16x16x32_bf16 v[34:37], v[194:197], v[210:213], v[34:37]
	v_mfma_f32_16x16x32_bf16 v[34:37], v[198:201], v[214:217], v[34:37]
	v_mfma_f32_16x16x32_bf16 v[38:41], v[190:193], v[214:217], v[38:41]
	v_mfma_f32_16x16x32_bf16 v[38:41], v[186:189], v[210:213], v[38:41]
	v_mfma_f32_16x16x32_bf16 v[22:25], v[186:189], v[218:221], v[22:25]
	v_mfma_f32_16x16x32_bf16 v[22:25], v[190:193], v[222:225], v[22:25]
	v_mfma_f32_16x16x32_bf16 v[18:21], v[198:201], v[222:225], v[18:21]
	v_mfma_f32_16x16x32_bf16 v[18:21], v[194:197], v[218:221], v[18:21]
	v_mfma_f32_16x16x32_bf16 v[2:5], v[194:197], v[226:229], v[2:5]
	v_mfma_f32_16x16x32_bf16 v[2:5], v[198:201], v[230:233], v[2:5]
	v_mfma_f32_16x16x32_bf16 v[6:9], v[190:193], v[230:233], v[6:9]
	v_mfma_f32_16x16x32_bf16 v[6:9], v[186:189], v[226:229], v[6:9]
	s_setprio 0
	s_barrier
	s_add_i32 s52, 0, 0x18000
	s_add_i32 s53, 0, 0x1c000
	v_add_u32_e32 v94, s52, v1
	v_add_u32_e32 v167, s53, v1
	ds_read_b128 v[82:85], v94
	ds_read_b128 v[86:89], v94 offset:1024
	ds_read_b128 v[90:93], v94 offset:2048
	ds_read_b128 v[94:97], v94 offset:3072
	ds_read_b128 v[186:189], v167
	ds_read_b128 v[190:193], v167 offset:1024
	ds_read_b128 v[194:197], v167 offset:2048
	ds_read_b128 v[198:201], v167 offset:3072
	s_add_u32 s34, s34, 0x100000
	s_addc_u32 s35, s35, 0
	s_mov_b32 m0, s38
	v_lshl_add_u64 v[242:243], s[34:35], 0, v[146:147]
	ds_read_b128 v[202:205], v180 offset:32768
	ds_read_b128 v[206:209], v180 offset:33792
	ds_read_b128 v[210:213], v180 offset:34816
	ds_read_b128 v[214:217], v180 offset:35840
	ds_read_b128 v[218:221], v180 offset:36864
	ds_read_b128 v[222:225], v180 offset:37888
	ds_read_b128 v[226:229], v180 offset:38912
	ds_read_b128 v[230:233], v180 offset:39936
	global_load_lds_dwordx4 v[242:243], off
	v_lshl_add_u64 v[242:243], s[34:35], 0, v[150:151]
	s_mov_b32 m0, s39
	s_nop 0
	global_load_lds_dwordx4 v[242:243], off
	s_waitcnt vmcnt(8)
	s_waitcnt lgkmcnt(0)
	s_barrier
	s_setprio 1
	s_waitcnt lgkmcnt(0)
	v_mfma_f32_16x16x32_bf16 v[142:145], v[82:85], v[202:205], v[142:145]
	v_mfma_f32_16x16x32_bf16 v[142:145], v[86:89], v[206:209], v[142:145]
	v_mfma_f32_16x16x32_bf16 v[138:141], v[94:97], v[206:209], v[138:141]
	v_mfma_f32_16x16x32_bf16 v[138:141], v[90:93], v[202:205], v[138:141]
	v_mfma_f32_16x16x32_bf16 v[122:125], v[90:93], v[210:213], v[122:125]
	v_mfma_f32_16x16x32_bf16 v[122:125], v[94:97], v[214:217], v[122:125]
	v_mfma_f32_16x16x32_bf16 v[126:129], v[86:89], v[214:217], v[126:129]
	v_mfma_f32_16x16x32_bf16 v[126:129], v[82:85], v[210:213], v[126:129]
	v_mfma_f32_16x16x32_bf16 v[110:113], v[82:85], v[218:221], v[110:113]
	v_mfma_f32_16x16x32_bf16 v[110:113], v[86:89], v[222:225], v[110:113]
	v_mfma_f32_16x16x32_bf16 v[106:109], v[94:97], v[222:225], v[106:109]
	v_mfma_f32_16x16x32_bf16 v[106:109], v[90:93], v[218:221], v[106:109]
	v_mfma_f32_16x16x32_bf16 v[74:77], v[90:93], v[226:229], v[74:77]
	v_mfma_f32_16x16x32_bf16 v[74:77], v[94:97], v[230:233], v[74:77]
	v_mfma_f32_16x16x32_bf16 v[78:81], v[86:89], v[230:233], v[78:81]
	v_mfma_f32_16x16x32_bf16 v[78:81], v[82:85], v[226:229], v[78:81]
	s_setprio 0
	s_setprio 1
	v_mfma_f32_16x16x32_bf16 v[134:137], v[186:189], v[202:205], v[134:137]
	v_mfma_f32_16x16x32_bf16 v[134:137], v[190:193], v[206:209], v[134:137]
	v_mfma_f32_16x16x32_bf16 v[130:133], v[198:201], v[206:209], v[130:133]
	v_mfma_f32_16x16x32_bf16 v[130:133], v[194:197], v[202:205], v[130:133]
	v_mfma_f32_16x16x32_bf16 v[114:117], v[194:197], v[210:213], v[114:117]
	v_mfma_f32_16x16x32_bf16 v[114:117], v[198:201], v[214:217], v[114:117]
	v_mfma_f32_16x16x32_bf16 v[118:121], v[190:193], v[214:217], v[118:121]
	v_mfma_f32_16x16x32_bf16 v[118:121], v[186:189], v[210:213], v[118:121]
	v_mfma_f32_16x16x32_bf16 v[102:105], v[186:189], v[218:221], v[102:105]
	v_mfma_f32_16x16x32_bf16 v[102:105], v[190:193], v[222:225], v[102:105]
	v_mfma_f32_16x16x32_bf16 v[98:101], v[198:201], v[222:225], v[98:101]
	v_mfma_f32_16x16x32_bf16 v[98:101], v[194:197], v[218:221], v[98:101]
	v_mfma_f32_16x16x32_bf16 v[66:69], v[194:197], v[226:229], v[66:69]
	v_mfma_f32_16x16x32_bf16 v[66:69], v[198:201], v[230:233], v[66:69]
	v_mfma_f32_16x16x32_bf16 v[70:73], v[190:193], v[230:233], v[70:73]
	v_mfma_f32_16x16x32_bf16 v[70:73], v[186:189], v[226:229], v[70:73]
	s_setprio 0
	s_barrier
; #define PG8_STAGE(bufoff, gbase, voff) do { _Pragma("unroll") for (int _i = 0; _i < 2; ++_i) \
;         __builtin_amdgcn_global_load_lds((const unsigned*)((const char*)(gbase) + (voff)[_i]), (PG8_LAS unsigned*)(lds + (bufoff) + ldsw + _i * 8192), 16, 0, 0); } while (0)
; #define PG8_LDA(dst, b, h) do { _Pragma("unroll") for (int m = 0; m < 4; ++m) _Pragma("unroll") for (int k = 0; k < 2; ++k) dst[m][k] = *(const PG8_LAS bf16x8*)(lds + PG8_SA(b, h) + aoff + m * 2048 + k * 1024); } while (0)
; #define PG8_MMA(ai, bj, At, Bt) do { __builtin_amdgcn_s_setprio(1); _Pragma("unroll") for (int m = 0; m < 4; ++m) _Pragma("unroll") for (int n = 0; n < 2; ++n) _Pragma("unroll") for (int k = 0; k < 2; ++k) \
;         acc[ai][bj][m][n] = __builtin_amdgcn_mfma_f32_16x16x32_bf16(Bt[n][k], At[m][k], acc[ai][bj][m][n], 0, 0, 0); __builtin_amdgcn_s_setprio(0); } while (0)
; #define PG8_WAIT_V(n) asm volatile("s_waitcnt vmcnt(" #n ")" ::: "memory")
; #define PG8_WAIT_L(n) asm volatile("s_waitcnt lgkmcnt(" #n ")" ::: "memory")
; #define PG8_BAR __builtin_amdgcn_s_barrier()
; #define PG8_SCHED __builtin_amdgcn_sched_barrier(0)
; template <class Epi, class Sched, bool ALIGN_EPI = false, bool SP2 = false>
; __device__ __forceinline__ void gemm_phase(PG8_LAS unsigned char* lds, const Gemm g, const Sched& S, const Epi& E) {
;     ...
;             PG8_LDA(At, 1, 1); PG8_STAGE(PG8_SB(1, 0), b3, voffB); PG8_STAGE(PG8_SB(1, 1), b3 + hstepB, voffB); PG8_STAGE(PG8_SA(1, 0), a3, voffA);
;             PG8_WAIT_V(8); PG8_WAIT_L(0); PG8_BAR; PG8_MMA(1, 0, At, B0); PG8_MMA(1, 1, At, B1); PG8_BAR; PG8_SCHED;
	s_add_i32 s34, s52, s37
	v_lshl_add_u64 v[234:235], v[234:235], 0, s[16:17]
	s_mov_b32 m0, s34
	ds_read_b128 v[202:205], v180 offset:49152
	ds_read_b128 v[206:209], v180 offset:50176
	ds_read_b128 v[210:213], v180 offset:51200
	ds_read_b128 v[214:217], v180 offset:52224
	ds_read_b128 v[218:221], v180 offset:53248
	ds_read_b128 v[222:225], v180 offset:54272
	ds_read_b128 v[226:229], v180 offset:55296
	ds_read_b128 v[230:233], v180 offset:56320
	global_load_lds_dwordx4 v[234:235], off
	s_add_i32 m0, s34, 0x2000
	s_add_u32 s10, s10, 0x40080
	v_lshl_add_u64 v[234:235], v[236:237], 0, s[16:17]
	s_addc_u32 s11, s11, 0
	s_add_i32 s34, s53, s37
	global_load_lds_dwordx4 v[234:235], off
	v_lshl_add_u64 v[234:235], s[10:11], 0, v[148:149]
	s_mov_b32 m0, s34
	s_nop 0
	global_load_lds_dwordx4 v[234:235], off
	v_lshl_add_u64 v[234:235], s[10:11], 0, v[152:153]
	s_add_i32 m0, s34, 0x2000
	s_nop 0
	global_load_lds_dwordx4 v[234:235], off
	v_lshl_add_u64 v[234:235], v[238:239], 0, s[16:17]
	s_mov_b32 m0, s40
	s_nop 0
	global_load_lds_dwordx4 v[234:235], off
	v_lshl_add_u64 v[234:235], v[240:241], 0, s[16:17]
	s_mov_b32 m0, s41
	s_nop 0
	global_load_lds_dwordx4 v[234:235], off
	s_waitcnt vmcnt(8)
	s_waitcnt lgkmcnt(0)
	s_barrier
	s_setprio 1
	s_waitcnt lgkmcnt(0)
	v_mfma_f32_16x16x32_bf16 v[62:65], v[82:85], v[202:205], v[62:65]
	v_mfma_f32_16x16x32_bf16 v[62:65], v[86:89], v[206:209], v[62:65]
	v_mfma_f32_16x16x32_bf16 v[58:61], v[94:97], v[206:209], v[58:61]
	v_mfma_f32_16x16x32_bf16 v[58:61], v[90:93], v[202:205], v[58:61]
	v_mfma_f32_16x16x32_bf16 v[42:45], v[90:93], v[210:213], v[42:45]
	v_mfma_f32_16x16x32_bf16 v[42:45], v[94:97], v[214:217], v[42:45]
	v_mfma_f32_16x16x32_bf16 v[46:49], v[86:89], v[214:217], v[46:49]
	v_mfma_f32_16x16x32_bf16 v[46:49], v[82:85], v[210:213], v[46:49]
	v_mfma_f32_16x16x32_bf16 v[30:33], v[82:85], v[218:221], v[30:33]
	v_mfma_f32_16x16x32_bf16 v[30:33], v[86:89], v[222:225], v[30:33]
	v_mfma_f32_16x16x32_bf16 v[26:29], v[94:97], v[222:225], v[26:29]
	v_mfma_f32_16x16x32_bf16 v[26:29], v[90:93], v[218:221], v[26:29]
	v_mfma_f32_16x16x32_bf16 v[10:13], v[90:93], v[226:229], v[10:13]
	v_mfma_f32_16x16x32_bf16 v[10:13], v[94:97], v[230:233], v[10:13]
	v_mfma_f32_16x16x32_bf16 v[14:17], v[86:89], v[230:233], v[14:17]
	v_mfma_f32_16x16x32_bf16 v[14:17], v[82:85], v[226:229], v[14:17]
	s_setprio 0
	s_setprio 1
	v_mfma_f32_16x16x32_bf16 v[54:57], v[186:189], v[202:205], v[54:57]
	v_mfma_f32_16x16x32_bf16 v[54:57], v[190:193], v[206:209], v[54:57]
	v_mfma_f32_16x16x32_bf16 v[50:53], v[198:201], v[206:209], v[50:53]
	v_mfma_f32_16x16x32_bf16 v[50:53], v[194:197], v[202:205], v[50:53]
	v_mfma_f32_16x16x32_bf16 v[34:37], v[194:197], v[210:213], v[34:37]
	v_mfma_f32_16x16x32_bf16 v[34:37], v[198:201], v[214:217], v[34:37]
	v_mfma_f32_16x16x32_bf16 v[38:41], v[190:193], v[214:217], v[38:41]
	v_mfma_f32_16x16x32_bf16 v[38:41], v[186:189], v[210:213], v[38:41]
	v_mfma_f32_16x16x32_bf16 v[22:25], v[186:189], v[218:221], v[22:25]
	v_mfma_f32_16x16x32_bf16 v[22:25], v[190:193], v[222:225], v[22:25]
	v_mfma_f32_16x16x32_bf16 v[18:21], v[198:201], v[222:225], v[18:21]
	v_mfma_f32_16x16x32_bf16 v[18:21], v[194:197], v[218:221], v[18:21]
	v_mfma_f32_16x16x32_bf16 v[2:5], v[194:197], v[226:229], v[2:5]
	v_mfma_f32_16x16x32_bf16 v[2:5], v[198:201], v[230:233], v[2:5]
	v_mfma_f32_16x16x32_bf16 v[6:9], v[190:193], v[230:233], v[6:9]
	v_mfma_f32_16x16x32_bf16 v[6:9], v[186:189], v[226:229], v[6:9]
	s_setprio 0
	s_barrier
	s_add_i32 s51, s51, 2
	s_add_u32 s6, s6, 0x100
	s_addc_u32 s7, s7, 0
	s_add_u32 s49, s49, 0x100
	s_addc_u32 s50, s50, 0
	s_cmp_gt_u32 s51, 61
	s_cbranch_scc0 .LBB0_402
	s_and_b64 vcc, exec, s[18:19]
	s_cbranch_vccz .LBB0_405
	s_barrier

; #define PG8_STAGE(bufoff, gbase, voff) do { _Pragma("unroll") for (int _i = 0; _i < 2; ++_i) \
;         __builtin_amdgcn_global_load_lds((const unsigned*)((const char*)(gbase) + (voff)[_i]), (PG8_LAS unsigned*)(lds + (bufoff) + ldsw + _i * 8192), 16, 0, 0); } while (0)
; #define PG8_LDA(dst, b, h) do { _Pragma("unroll") for (int m = 0; m < 4; ++m) _Pragma("unroll") for (int k = 0; k < 2; ++k) dst[m][k] = *(const PG8_LAS bf16x8*)(lds + PG8_SA(b, h) + aoff + m * 2048 + k * 1024); } while (0)
; #define PG8_LDB(dst, b, h) do { _Pragma("unroll") for (int n = 0; n < 2; ++n) _Pragma("unroll") for (int k = 0; k < 2; ++k) dst[n][k] = *(const PG8_LAS bf16x8*)(lds + PG8_SB(b, h) + boff + n * 2048 + k * 1024); } while (0)
; #define PG8_MMA(ai, bj, At, Bt) do { __builtin_amdgcn_s_setprio(1); _Pragma("unroll") for (int m = 0; m < 4; ++m) _Pragma("unroll") for (int n = 0; n < 2; ++n) _Pragma("unroll") for (int k = 0; k < 2; ++k) \
;         acc[ai][bj][m][n] = __builtin_amdgcn_mfma_f32_16x16x32_bf16(Bt[n][k], At[m][k], acc[ai][bj][m][n], 0, 0, 0); __builtin_amdgcn_s_setprio(0); } while (0)
; #define PG8_WAIT_V(n) asm volatile("s_waitcnt vmcnt(" #n ")" ::: "memory")
; #define PG8_WAIT_L(n) asm volatile("s_waitcnt lgkmcnt(" #n ")" ::: "memory")
; #define PG8_BAR __builtin_amdgcn_s_barrier()
; #define PG8_SCHED __builtin_amdgcn_sched_barrier(0)
; template <class Epi, class Sched, bool ALIGN_EPI = false, bool SP2 = false>
; __device__ __forceinline__ void gemm_phase(PG8_LAS unsigned char* lds, const Gemm g, const Sched& S, const Epi& E) {
;     ...
;             PG8_LDB(B0, 0, 0); PG8_LDB(B1, 0, 1); PG8_SCHED; PG8_LDA(At, 0, 0); PG8_STAGE(PG8_SA(1, 1), a1 + hstep, voffA);
;             PG8_WAIT_V(8); PG8_WAIT_L(0); PG8_BAR; PG8_MMA(0, 0, At, B0); PG8_MMA(0, 1, At, B1); PG8_BAR; PG8_SCHED;
;             PG8_LDA(At, 0, 1); PG8_STAGE(PG8_SB(0, 0), b2, voffB); PG8_STAGE(PG8_SB(0, 1), b2 + hstepB, voffB); PG8_STAGE(PG8_SA(0, 0), a2, voffA);
;             PG8_WAIT_V(8); PG8_WAIT_L(0); PG8_BAR; PG8_MMA(1, 0, At, B0); PG8_MMA(1, 1, At, B1); PG8_BAR; PG8_SCHED;
.LBB0_1759:
	ds_read_b128 v[66:69], v168
	ds_read_b128 v[70:73], v168 offset:1024
	ds_read_b128 v[74:77], v168 offset:2048
	ds_read_b128 v[78:81], v168 offset:3072
	ds_read_b128 v[162:165], v169
	ds_read_b128 v[172:175], v169 offset:1024
	ds_read_b128 v[176:179], v169 offset:2048
	ds_read_b128 v[180:183], v169 offset:3072
	s_add_u32 s34, s30, 0xfff00080
	s_addc_u32 s35, s31, -1
	s_cmp_eq_u32 s63, 60
	s_cselect_b32 s37, s23, s35
	s_cselect_b32 s36, s59, s34
	s_cselect_b32 s35, s21, s62
	s_cselect_b32 s34, s60, s61
	v_lshl_add_u64 v[216:217], s[30:31], 0, v[154:155]
	s_add_i32 m0, s40, 0xc000
	ds_read_b128 v[184:187], v170
	ds_read_b128 v[188:191], v170 offset:1024
	ds_read_b128 v[192:195], v170 offset:2048
	ds_read_b128 v[196:199], v170 offset:3072
	ds_read_b128 v[200:203], v170 offset:4096
	ds_read_b128 v[204:207], v170 offset:5120
	ds_read_b128 v[208:211], v170 offset:6144
	ds_read_b128 v[212:215], v170 offset:7168
	global_load_lds_dwordx4 v[216:217], off
	v_lshl_add_u64 v[216:217], s[30:31], 0, v[156:157]
	s_add_i32 m0, s40, 0xe000
	s_nop 0
	global_load_lds_dwordx4 v[216:217], off
	s_waitcnt vmcnt(8)
	s_waitcnt lgkmcnt(0)
	s_barrier
	s_setprio 1
	s_waitcnt lgkmcnt(0)
	v_mfma_f32_16x16x32_bf16 v[142:145], v[66:69], v[184:187], v[142:145]
	v_mfma_f32_16x16x32_bf16 v[142:145], v[70:73], v[188:191], v[142:145]
	v_mfma_f32_16x16x32_bf16 v[138:141], v[78:81], v[188:191], v[138:141]
	v_mfma_f32_16x16x32_bf16 v[138:141], v[74:77], v[184:187], v[138:141]
	v_mfma_f32_16x16x32_bf16 v[122:125], v[74:77], v[192:195], v[122:125]
	v_mfma_f32_16x16x32_bf16 v[122:125], v[78:81], v[196:199], v[122:125]
	v_mfma_f32_16x16x32_bf16 v[126:129], v[70:73], v[196:199], v[126:129]
	v_mfma_f32_16x16x32_bf16 v[126:129], v[66:69], v[192:195], v[126:129]
	v_mfma_f32_16x16x32_bf16 v[110:113], v[66:69], v[200:203], v[110:113]
	v_mfma_f32_16x16x32_bf16 v[110:113], v[70:73], v[204:207], v[110:113]
	v_mfma_f32_16x16x32_bf16 v[106:109], v[78:81], v[204:207], v[106:109]
	v_mfma_f32_16x16x32_bf16 v[106:109], v[74:77], v[200:203], v[106:109]
	v_mfma_f32_16x16x32_bf16 v[90:93], v[74:77], v[208:211], v[90:93]
	v_mfma_f32_16x16x32_bf16 v[90:93], v[78:81], v[212:215], v[90:93]
	v_mfma_f32_16x16x32_bf16 v[94:97], v[70:73], v[212:215], v[94:97]
	v_mfma_f32_16x16x32_bf16 v[94:97], v[66:69], v[208:211], v[94:97]
	s_setprio 0
	s_setprio 1
	v_mfma_f32_16x16x32_bf16 v[134:137], v[162:165], v[184:187], v[134:137]
	v_mfma_f32_16x16x32_bf16 v[134:137], v[172:175], v[188:191], v[134:137]
	v_mfma_f32_16x16x32_bf16 v[130:133], v[180:183], v[188:191], v[130:133]
	v_mfma_f32_16x16x32_bf16 v[130:133], v[176:179], v[184:187], v[130:133]
	v_mfma_f32_16x16x32_bf16 v[114:117], v[176:179], v[192:195], v[114:117]
	v_mfma_f32_16x16x32_bf16 v[114:117], v[180:183], v[196:199], v[114:117]
	v_mfma_f32_16x16x32_bf16 v[118:121], v[172:175], v[196:199], v[118:121]
	v_mfma_f32_16x16x32_bf16 v[118:121], v[162:165], v[192:195], v[118:121]
	v_mfma_f32_16x16x32_bf16 v[102:105], v[162:165], v[200:203], v[102:105]
	v_mfma_f32_16x16x32_bf16 v[102:105], v[172:175], v[204:207], v[102:105]
	v_mfma_f32_16x16x32_bf16 v[98:101], v[180:183], v[204:207], v[98:101]
	v_mfma_f32_16x16x32_bf16 v[98:101], v[176:179], v[200:203], v[98:101]
	v_mfma_f32_16x16x32_bf16 v[82:85], v[176:179], v[208:211], v[82:85]
	v_mfma_f32_16x16x32_bf16 v[82:85], v[180:183], v[212:215], v[82:85]
	v_mfma_f32_16x16x32_bf16 v[86:89], v[172:175], v[212:215], v[86:89]
	v_mfma_f32_16x16x32_bf16 v[86:89], v[162:165], v[208:211], v[86:89]
	s_setprio 0
	s_barrier
	s_add_i32 s64, s50, s39
	v_lshl_add_u64 v[216:217], s[34:35], 0, v[148:149]
	s_mov_b32 m0, s64
	ds_read_b128 v[184:187], v170 offset:16384
	ds_read_b128 v[188:191], v170 offset:17408
	ds_read_b128 v[192:195], v170 offset:18432
	ds_read_b128 v[196:199], v170 offset:19456
	ds_read_b128 v[200:203], v170 offset:20480
	ds_read_b128 v[204:207], v170 offset:21504
	ds_read_b128 v[208:211], v170 offset:22528
	ds_read_b128 v[212:215], v170 offset:23552
	global_load_lds_dwordx4 v[216:217], off
	s_add_i32 m0, s64, 0x2000
	s_add_u32 s64, s34, 0x100000
	v_lshl_add_u64 v[218:219], s[34:35], 0, v[152:153]
	s_addc_u32 s65, s35, 0
	s_add_i32 s66, s51, s39
	global_load_lds_dwordx4 v[218:219], off
	v_lshl_add_u64 v[220:221], s[64:65], 0, v[148:149]
	s_mov_b32 m0, s66
	v_lshl_add_u64 v[222:223], s[36:37], 0, v[150:151]
	global_load_lds_dwordx4 v[220:221], off
	v_lshl_add_u64 v[220:221], s[64:65], 0, v[152:153]
	s_add_i32 m0, s66, 0x2000
	s_nop 0
	global_load_lds_dwordx4 v[220:221], off
	v_lshl_add_u64 v[220:221], s[36:37], 0, v[146:147]
	s_mov_b32 m0, s40
	s_nop 0
	global_load_lds_dwordx4 v[220:221], off
	s_mov_b32 m0, s41
	s_nop 0
	global_load_lds_dwordx4 v[222:223], off
	s_waitcnt vmcnt(8)
	s_waitcnt lgkmcnt(0)
	s_barrier
; #define PG8_STAGE(bufoff, gbase, voff) do { _Pragma("unroll") for (int _i = 0; _i < 2; ++_i) \
;         __builtin_amdgcn_global_load_lds((const unsigned*)((const char*)(gbase) + (voff)[_i]), (PG8_LAS unsigned*)(lds + (bufoff) + ldsw + _i * 8192), 16, 0, 0); } while (0)
; #define PG8_LDA(dst, b, h) do { _Pragma("unroll") for (int m = 0; m < 4; ++m) _Pragma("unroll") for (int k = 0; k < 2; ++k) dst[m][k] = *(const PG8_LAS bf16x8*)(lds + PG8_SA(b, h) + aoff + m * 2048 + k * 1024); } while (0)
; #define PG8_LDB(dst, b, h) do { _Pragma("unroll") for (int n = 0; n < 2; ++n) _Pragma("unroll") for (int k = 0; k < 2; ++k) dst[n][k] = *(const PG8_LAS bf16x8*)(lds + PG8_SB(b, h) + boff + n * 2048 + k * 1024); } while (0)
; #define PG8_MMA(ai, bj, At, Bt) do { __builtin_amdgcn_s_setprio(1); _Pragma("unroll") for (int m = 0; m < 4; ++m) _Pragma("unroll") for (int n = 0; n < 2; ++n) _Pragma("unroll") for (int k = 0; k < 2; ++k) \
;         acc[ai][bj][m][n] = __builtin_amdgcn_mfma_f32_16x16x32_bf16(Bt[n][k], At[m][k], acc[ai][bj][m][n], 0, 0, 0); __builtin_amdgcn_s_setprio(0); } while (0)
; #define PG8_WAIT_V(n) asm volatile("s_waitcnt vmcnt(" #n ")" ::: "memory")
; #define PG8_WAIT_L(n) asm volatile("s_waitcnt lgkmcnt(" #n ")" ::: "memory")
; #define PG8_BAR __builtin_amdgcn_s_barrier()
; #define PG8_SCHED __builtin_amdgcn_sched_barrier(0)
; template <class Epi, class Sched, bool ALIGN_EPI = false, bool SP2 = false>
; __device__ __forceinline__ void gemm_phase(PG8_LAS unsigned char* lds, const Gemm g, const Sched& S, const Epi& E) {
;     ...
;             PG8_WAIT_V(8); PG8_WAIT_L(0); PG8_BAR; PG8_MMA(1, 0, At, B0); PG8_MMA(1, 1, At, B1); PG8_BAR; PG8_SCHED;
;             PG8_LDB(B0, 1, 0); PG8_LDB(B1, 1, 1); PG8_SCHED; PG8_LDA(At, 1, 0); PG8_STAGE(PG8_SA(0, 1), a2 + hstep, voffA);
;             PG8_WAIT_V(8); PG8_WAIT_L(0); PG8_BAR; PG8_MMA(0, 0, At, B0); PG8_MMA(0, 1, At, B1); PG8_BAR; PG8_SCHED;
	s_setprio 1
	s_waitcnt lgkmcnt(0)
	v_mfma_f32_16x16x32_bf16 v[62:65], v[66:69], v[184:187], v[62:65]
	v_mfma_f32_16x16x32_bf16 v[62:65], v[70:73], v[188:191], v[62:65]
	v_mfma_f32_16x16x32_bf16 v[58:61], v[78:81], v[188:191], v[58:61]
	v_mfma_f32_16x16x32_bf16 v[58:61], v[74:77], v[184:187], v[58:61]
	v_mfma_f32_16x16x32_bf16 v[42:45], v[74:77], v[192:195], v[42:45]
	v_mfma_f32_16x16x32_bf16 v[42:45], v[78:81], v[196:199], v[42:45]
	v_mfma_f32_16x16x32_bf16 v[46:49], v[70:73], v[196:199], v[46:49]
	v_mfma_f32_16x16x32_bf16 v[46:49], v[66:69], v[192:195], v[46:49]
	v_mfma_f32_16x16x32_bf16 v[30:33], v[66:69], v[200:203], v[30:33]
	v_mfma_f32_16x16x32_bf16 v[30:33], v[70:73], v[204:207], v[30:33]
	v_mfma_f32_16x16x32_bf16 v[26:29], v[78:81], v[204:207], v[26:29]
	v_mfma_f32_16x16x32_bf16 v[26:29], v[74:77], v[200:203], v[26:29]
	v_mfma_f32_16x16x32_bf16 v[18:21], v[74:77], v[208:211], v[18:21]
	v_mfma_f32_16x16x32_bf16 v[18:21], v[78:81], v[212:215], v[18:21]
	v_mfma_f32_16x16x32_bf16 v[22:25], v[70:73], v[212:215], v[22:25]
	v_mfma_f32_16x16x32_bf16 v[22:25], v[66:69], v[208:211], v[22:25]
	s_setprio 0
	s_setprio 1
	v_mfma_f32_16x16x32_bf16 v[54:57], v[162:165], v[184:187], v[54:57]
	v_mfma_f32_16x16x32_bf16 v[54:57], v[172:175], v[188:191], v[54:57]
	v_mfma_f32_16x16x32_bf16 v[50:53], v[180:183], v[188:191], v[50:53]
	v_mfma_f32_16x16x32_bf16 v[50:53], v[176:179], v[184:187], v[50:53]
	v_mfma_f32_16x16x32_bf16 v[34:37], v[176:179], v[192:195], v[34:37]
	v_mfma_f32_16x16x32_bf16 v[34:37], v[180:183], v[196:199], v[34:37]
	v_mfma_f32_16x16x32_bf16 v[38:41], v[172:175], v[196:199], v[38:41]
	v_mfma_f32_16x16x32_bf16 v[38:41], v[162:165], v[192:195], v[38:41]
	v_mfma_f32_16x16x32_bf16 v[14:17], v[162:165], v[200:203], v[14:17]
	v_mfma_f32_16x16x32_bf16 v[14:17], v[172:175], v[204:207], v[14:17]
	v_mfma_f32_16x16x32_bf16 v[10:13], v[180:183], v[204:207], v[10:13]
	v_mfma_f32_16x16x32_bf16 v[10:13], v[176:179], v[200:203], v[10:13]
	v_mfma_f32_16x16x32_bf16 v[2:5], v[176:179], v[208:211], v[2:5]
	v_mfma_f32_16x16x32_bf16 v[2:5], v[180:183], v[212:215], v[2:5]
	v_mfma_f32_16x16x32_bf16 v[6:9], v[172:175], v[212:215], v[6:9]
	v_mfma_f32_16x16x32_bf16 v[6:9], v[162:165], v[208:211], v[6:9]
	s_setprio 0
	s_barrier
	s_add_i32 s64, 0, 0x18000
	s_add_i32 s65, 0, 0x1c000
	v_add_u32_e32 v78, s64, v166
	v_add_u32_e32 v171, s65, v166
	ds_read_b128 v[66:69], v78
	ds_read_b128 v[70:73], v78 offset:1024
	ds_read_b128 v[74:77], v78 offset:2048
	ds_read_b128 v[78:81], v78 offset:3072
	ds_read_b128 v[162:165], v171
	ds_read_b128 v[172:175], v171 offset:1024
	ds_read_b128 v[176:179], v171 offset:2048
	ds_read_b128 v[180:183], v171 offset:3072
	s_add_u32 s36, s36, 0x100000
	s_addc_u32 s37, s37, 0
	s_mov_b32 m0, s42
	v_lshl_add_u64 v[224:225], s[36:37], 0, v[146:147]
	ds_read_b128 v[184:187], v170 offset:32768
	ds_read_b128 v[188:191], v170 offset:33792
	ds_read_b128 v[192:195], v170 offset:34816
	ds_read_b128 v[196:199], v170 offset:35840
	ds_read_b128 v[200:203], v170 offset:36864
	ds_read_b128 v[204:207], v170 offset:37888
	ds_read_b128 v[208:211], v170 offset:38912
	ds_read_b128 v[212:215], v170 offset:39936
	global_load_lds_dwordx4 v[224:225], off
	v_lshl_add_u64 v[224:225], s[36:37], 0, v[150:151]
	s_mov_b32 m0, s43
	s_nop 0
	global_load_lds_dwordx4 v[224:225], off
	s_waitcnt vmcnt(8)
	s_waitcnt lgkmcnt(0)
	s_barrier
	s_setprio 1
	s_waitcnt lgkmcnt(0)
	v_mfma_f32_16x16x32_bf16 v[142:145], v[66:69], v[184:187], v[142:145]
	v_mfma_f32_16x16x32_bf16 v[142:145], v[70:73], v[188:191], v[142:145]
	v_mfma_f32_16x16x32_bf16 v[138:141], v[78:81], v[188:191], v[138:141]
	v_mfma_f32_16x16x32_bf16 v[138:141], v[74:77], v[184:187], v[138:141]
	v_mfma_f32_16x16x32_bf16 v[122:125], v[74:77], v[192:195], v[122:125]
	v_mfma_f32_16x16x32_bf16 v[122:125], v[78:81], v[196:199], v[122:125]
	v_mfma_f32_16x16x32_bf16 v[126:129], v[70:73], v[196:199], v[126:129]
	v_mfma_f32_16x16x32_bf16 v[126:129], v[66:69], v[192:195], v[126:129]
	v_mfma_f32_16x16x32_bf16 v[110:113], v[66:69], v[200:203], v[110:113]
	v_mfma_f32_16x16x32_bf16 v[110:113], v[70:73], v[204:207], v[110:113]
	v_mfma_f32_16x16x32_bf16 v[106:109], v[78:81], v[204:207], v[106:109]
	v_mfma_f32_16x16x32_bf16 v[106:109], v[74:77], v[200:203], v[106:109]
	v_mfma_f32_16x16x32_bf16 v[90:93], v[74:77], v[208:211], v[90:93]
	v_mfma_f32_16x16x32_bf16 v[90:93], v[78:81], v[212:215], v[90:93]
	v_mfma_f32_16x16x32_bf16 v[94:97], v[70:73], v[212:215], v[94:97]
	v_mfma_f32_16x16x32_bf16 v[94:97], v[66:69], v[208:211], v[94:97]
	s_setprio 0
	s_setprio 1
	v_mfma_f32_16x16x32_bf16 v[134:137], v[162:165], v[184:187], v[134:137]
	v_mfma_f32_16x16x32_bf16 v[134:137], v[172:175], v[188:191], v[134:137]
	v_mfma_f32_16x16x32_bf16 v[130:133], v[180:183], v[188:191], v[130:133]
	v_mfma_f32_16x16x32_bf16 v[130:133], v[176:179], v[184:187], v[130:133]
	v_mfma_f32_16x16x32_bf16 v[114:117], v[176:179], v[192:195], v[114:117]
	v_mfma_f32_16x16x32_bf16 v[114:117], v[180:183], v[196:199], v[114:117]
	v_mfma_f32_16x16x32_bf16 v[118:121], v[172:175], v[196:199], v[118:121]
	v_mfma_f32_16x16x32_bf16 v[118:121], v[162:165], v[192:195], v[118:121]
	v_mfma_f32_16x16x32_bf16 v[102:105], v[162:165], v[200:203], v[102:105]
	v_mfma_f32_16x16x32_bf16 v[102:105], v[172:175], v[204:207], v[102:105]
	v_mfma_f32_16x16x32_bf16 v[98:101], v[180:183], v[204:207], v[98:101]
	v_mfma_f32_16x16x32_bf16 v[98:101], v[176:179], v[200:203], v[98:101]
	v_mfma_f32_16x16x32_bf16 v[82:85], v[176:179], v[208:211], v[82:85]
	v_mfma_f32_16x16x32_bf16 v[82:85], v[180:183], v[212:215], v[82:85]
	v_mfma_f32_16x16x32_bf16 v[86:89], v[172:175], v[212:215], v[86:89]
	v_mfma_f32_16x16x32_bf16 v[86:89], v[162:165], v[208:211], v[86:89]
	s_setprio 0
	s_barrier
; #define PG8_STAGE(bufoff, gbase, voff) do { _Pragma("unroll") for (int _i = 0; _i < 2; ++_i) \
;         __builtin_amdgcn_global_load_lds((const unsigned*)((const char*)(gbase) + (voff)[_i]), (PG8_LAS unsigned*)(lds + (bufoff) + ldsw + _i * 8192), 16, 0, 0); } while (0)
; #define PG8_LDA(dst, b, h) do { _Pragma("unroll") for (int m = 0; m < 4; ++m) _Pragma("unroll") for (int k = 0; k < 2; ++k) dst[m][k] = *(const PG8_LAS bf16x8*)(lds + PG8_SA(b, h) + aoff + m * 2048 + k * 1024); } while (0)
; #define PG8_MMA(ai, bj, At, Bt) do { __builtin_amdgcn_s_setprio(1); _Pragma("unroll") for (int m = 0; m < 4; ++m) _Pragma("unroll") for (int n = 0; n < 2; ++n) _Pragma("unroll") for (int k = 0; k < 2; ++k) \
;         acc[ai][bj][m][n] = __builtin_amdgcn_mfma_f32_16x16x32_bf16(Bt[n][k], At[m][k], acc[ai][bj][m][n], 0, 0, 0); __builtin_amdgcn_s_setprio(0); } while (0)
; #define PG8_WAIT_V(n) asm volatile("s_waitcnt vmcnt(" #n ")" ::: "memory")
; #define PG8_WAIT_L(n) asm volatile("s_waitcnt lgkmcnt(" #n ")" ::: "memory")
; #define PG8_BAR __builtin_amdgcn_s_barrier()
; #define PG8_SCHED __builtin_amdgcn_sched_barrier(0)
; template <class Epi, class Sched, bool ALIGN_EPI = false, bool SP2 = false>
; __device__ __forceinline__ void gemm_phase(PG8_LAS unsigned char* lds, const Gemm g, const Sched& S, const Epi& E) {
;     ...
;             PG8_LDA(At, 1, 1); PG8_STAGE(PG8_SB(1, 0), b3, voffB); PG8_STAGE(PG8_SB(1, 1), b3 + hstepB, voffB); PG8_STAGE(PG8_SA(1, 0), a3, voffA);
;             PG8_WAIT_V(8); PG8_WAIT_L(0); PG8_BAR; PG8_MMA(1, 0, At, B0); PG8_MMA(1, 1, At, B1); PG8_BAR; PG8_SCHED;
	s_add_i32 s36, s64, s39
	v_lshl_add_u64 v[216:217], v[216:217], 0, s[6:7]
	s_mov_b32 m0, s36
	ds_read_b128 v[184:187], v170 offset:49152
	ds_read_b128 v[188:191], v170 offset:50176
	ds_read_b128 v[192:195], v170 offset:51200
	ds_read_b128 v[196:199], v170 offset:52224
	ds_read_b128 v[200:203], v170 offset:53248
	ds_read_b128 v[204:207], v170 offset:54272
	ds_read_b128 v[208:211], v170 offset:55296
	ds_read_b128 v[212:215], v170 offset:56320
	global_load_lds_dwordx4 v[216:217], off
	s_add_i32 m0, s36, 0x2000
	s_add_u32 s34, s34, 0x100080
	v_lshl_add_u64 v[216:217], v[218:219], 0, s[6:7]
	s_addc_u32 s35, s35, 0
	s_add_i32 s36, s65, s39
	global_load_lds_dwordx4 v[216:217], off
	v_lshl_add_u64 v[216:217], s[34:35], 0, v[148:149]
	s_mov_b32 m0, s36
	s_nop 0
	global_load_lds_dwordx4 v[216:217], off
	v_lshl_add_u64 v[216:217], s[34:35], 0, v[152:153]
	s_add_i32 m0, s36, 0x2000
	s_nop 0
	global_load_lds_dwordx4 v[216:217], off
	v_lshl_add_u64 v[216:217], v[220:221], 0, s[6:7]
	s_mov_b32 m0, s47
	s_nop 0
	global_load_lds_dwordx4 v[216:217], off
	v_lshl_add_u64 v[216:217], v[222:223], 0, s[6:7]
	s_mov_b32 m0, s48
	s_nop 0
	global_load_lds_dwordx4 v[216:217], off
	s_waitcnt vmcnt(8)
	s_waitcnt lgkmcnt(0)
	s_barrier
	s_setprio 1
	s_waitcnt lgkmcnt(0)
	v_mfma_f32_16x16x32_bf16 v[62:65], v[66:69], v[184:187], v[62:65]
	v_mfma_f32_16x16x32_bf16 v[62:65], v[70:73], v[188:191], v[62:65]
	v_mfma_f32_16x16x32_bf16 v[58:61], v[78:81], v[188:191], v[58:61]
	v_mfma_f32_16x16x32_bf16 v[58:61], v[74:77], v[184:187], v[58:61]
	v_mfma_f32_16x16x32_bf16 v[42:45], v[74:77], v[192:195], v[42:45]
	v_mfma_f32_16x16x32_bf16 v[42:45], v[78:81], v[196:199], v[42:45]
	v_mfma_f32_16x16x32_bf16 v[46:49], v[70:73], v[196:199], v[46:49]
	v_mfma_f32_16x16x32_bf16 v[46:49], v[66:69], v[192:195], v[46:49]
	v_mfma_f32_16x16x32_bf16 v[30:33], v[66:69], v[200:203], v[30:33]
	v_mfma_f32_16x16x32_bf16 v[30:33], v[70:73], v[204:207], v[30:33]
	v_mfma_f32_16x16x32_bf16 v[26:29], v[78:81], v[204:207], v[26:29]
	v_mfma_f32_16x16x32_bf16 v[26:29], v[74:77], v[200:203], v[26:29]
	v_mfma_f32_16x16x32_bf16 v[18:21], v[74:77], v[208:211], v[18:21]
	v_mfma_f32_16x16x32_bf16 v[18:21], v[78:81], v[212:215], v[18:21]
	v_mfma_f32_16x16x32_bf16 v[22:25], v[70:73], v[212:215], v[22:25]
	v_mfma_f32_16x16x32_bf16 v[22:25], v[66:69], v[208:211], v[22:25]
	s_setprio 0
	s_setprio 1
	v_mfma_f32_16x16x32_bf16 v[54:57], v[162:165], v[184:187], v[54:57]
	v_mfma_f32_16x16x32_bf16 v[54:57], v[172:175], v[188:191], v[54:57]
	v_mfma_f32_16x16x32_bf16 v[50:53], v[180:183], v[188:191], v[50:53]
	v_mfma_f32_16x16x32_bf16 v[50:53], v[176:179], v[184:187], v[50:53]
	v_mfma_f32_16x16x32_bf16 v[34:37], v[176:179], v[192:195], v[34:37]
	v_mfma_f32_16x16x32_bf16 v[34:37], v[180:183], v[196:199], v[34:37]
	v_mfma_f32_16x16x32_bf16 v[38:41], v[172:175], v[196:199], v[38:41]
	v_mfma_f32_16x16x32_bf16 v[38:41], v[162:165], v[192:195], v[38:41]
	v_mfma_f32_16x16x32_bf16 v[14:17], v[162:165], v[200:203], v[14:17]
	v_mfma_f32_16x16x32_bf16 v[14:17], v[172:175], v[204:207], v[14:17]
	v_mfma_f32_16x16x32_bf16 v[10:13], v[180:183], v[204:207], v[10:13]
	v_mfma_f32_16x16x32_bf16 v[10:13], v[176:179], v[200:203], v[10:13]
	v_mfma_f32_16x16x32_bf16 v[2:5], v[176:179], v[208:211], v[2:5]
	v_mfma_f32_16x16x32_bf16 v[2:5], v[180:183], v[212:215], v[2:5]
	v_mfma_f32_16x16x32_bf16 v[6:9], v[172:175], v[212:215], v[6:9]
	v_mfma_f32_16x16x32_bf16 v[6:9], v[162:165], v[208:211], v[6:9]
	s_setprio 0
	s_barrier
	s_add_i32 s63, s63, 2
	s_add_u32 s30, s30, 0x100
	s_addc_u32 s31, s31, 0
	s_add_u32 s61, s61, 0x100
	s_addc_u32 s62, s62, 0
	s_cmp_gt_u32 s63, 61
	s_cbranch_scc0 .LBB0_1759
	s_and_b64 vcc, exec, s[8:9]
	s_cbranch_vccz .LBB0_1762
	s_barrier

; #define PG8_STAGE(bufoff, gbase, voff) do { _Pragma("unroll") for (int _i = 0; _i < 2; ++_i) \
;         __builtin_amdgcn_global_load_lds((const unsigned*)((const char*)(gbase) + (voff)[_i]), (PG8_LAS unsigned*)(lds + (bufoff) + ldsw + _i * 8192), 16, 0, 0); } while (0)
; #define PG8_LDA(dst, b, h) do { _Pragma("unroll") for (int m = 0; m < 4; ++m) _Pragma("unroll") for (int k = 0; k < 2; ++k) dst[m][k] = *(const PG8_LAS bf16x8*)(lds + PG8_SA(b, h) + aoff + m * 2048 + k * 1024); } while (0)
; #define PG8_LDB(dst, b, h) do { _Pragma("unroll") for (int n = 0; n < 2; ++n) _Pragma("unroll") for (int k = 0; k < 2; ++k) dst[n][k] = *(const PG8_LAS bf16x8*)(lds + PG8_SB(b, h) + boff + n * 2048 + k * 1024); } while (0)
; #define PG8_MMA(ai, bj, At, Bt) do { __builtin_amdgcn_s_setprio(1); _Pragma("unroll") for (int m = 0; m < 4; ++m) _Pragma("unroll") for (int n = 0; n < 2; ++n) _Pragma("unroll") for (int k = 0; k < 2; ++k) \
;         acc[ai][bj][m][n] = __builtin_amdgcn_mfma_f32_16x16x32_bf16(Bt[n][k], At[m][k], acc[ai][bj][m][n], 0, 0, 0); __builtin_amdgcn_s_setprio(0); } while (0)
; #define PG8_WAIT_V(n) asm volatile("s_waitcnt vmcnt(" #n ")" ::: "memory")
; #define PG8_WAIT_L(n) asm volatile("s_waitcnt lgkmcnt(" #n ")" ::: "memory")
; #define PG8_BAR __builtin_amdgcn_s_barrier()
; #define PG8_SCHED __builtin_amdgcn_sched_barrier(0)
; template <class Epi, class Sched, bool ALIGN_EPI = false, bool SP2 = false>
; __device__ __forceinline__ void gemm_phase(PG8_LAS unsigned char* lds, const Gemm g, const Sched& S, const Epi& E) {
;     ...
;             PG8_LDB(B0, 0, 0); PG8_LDB(B1, 0, 1); PG8_SCHED; PG8_LDA(At, 0, 0); PG8_STAGE(PG8_SA(1, 1), a1 + hstep, voffA);
;             PG8_WAIT_V(8); PG8_WAIT_L(0); PG8_BAR; PG8_MMA(0, 0, At, B0); PG8_MMA(0, 1, At, B1); PG8_BAR; PG8_SCHED;
;             PG8_LDA(At, 0, 1); PG8_STAGE(PG8_SB(0, 0), b2, voffB); PG8_STAGE(PG8_SB(0, 1), b2 + hstepB, voffB); PG8_STAGE(PG8_SA(0, 0), a2, voffA);
;             PG8_WAIT_V(8); PG8_WAIT_L(0); PG8_BAR; PG8_MMA(1, 0, At, B0); PG8_MMA(1, 1, At, B1); PG8_BAR; PG8_SCHED;
.LBB0_1889:
	ds_read_b128 v[146:149], v152
	ds_read_b128 v[156:159], v152 offset:1024
	ds_read_b128 v[160:163], v152 offset:2048
	ds_read_b128 v[164:167], v152 offset:3072
	ds_read_b128 v[168:171], v153
	ds_read_b128 v[172:175], v153 offset:1024
	ds_read_b128 v[176:179], v153 offset:2048
	ds_read_b128 v[180:183], v153 offset:3072
	s_add_u32 s16, s14, 0x100
	s_addc_u32 s17, s15, 0
	s_cmp_eq_u32 s44, 60
	s_cselect_b32 s21, s5, s17
	s_cselect_b32 s20, s4, s16
	s_cselect_b32 s19, s13, s43
	s_cselect_b32 s18, s12, s42
	v_lshl_add_u64 v[216:217], s[14:15], 0, v[138:139]
	s_add_i32 m0, s26, 0xc000
	ds_read_b128 v[184:187], v154
	ds_read_b128 v[188:191], v154 offset:1024
	ds_read_b128 v[192:195], v154 offset:2048
	ds_read_b128 v[196:199], v154 offset:3072
	ds_read_b128 v[200:203], v154 offset:4096
	ds_read_b128 v[204:207], v154 offset:5120
	ds_read_b128 v[208:211], v154 offset:6144
	ds_read_b128 v[212:215], v154 offset:7168
	global_load_lds_dwordx4 v[216:217], off
	v_lshl_add_u64 v[216:217], s[14:15], 0, v[140:141]
	s_add_i32 m0, s26, 0xe000
	s_nop 0
	global_load_lds_dwordx4 v[216:217], off
	s_waitcnt vmcnt(8)
	s_waitcnt lgkmcnt(0)
	s_barrier
	s_setprio 1
	s_waitcnt lgkmcnt(0)
	v_mfma_f32_16x16x32_bf16 v[126:129], v[146:149], v[184:187], v[126:129]
	v_mfma_f32_16x16x32_bf16 v[126:129], v[156:159], v[188:191], v[126:129]
	v_mfma_f32_16x16x32_bf16 v[122:125], v[164:167], v[188:191], v[122:125]
	v_mfma_f32_16x16x32_bf16 v[122:125], v[160:163], v[184:187], v[122:125]
	v_mfma_f32_16x16x32_bf16 v[106:109], v[160:163], v[192:195], v[106:109]
	v_mfma_f32_16x16x32_bf16 v[106:109], v[164:167], v[196:199], v[106:109]
	v_mfma_f32_16x16x32_bf16 v[110:113], v[156:159], v[196:199], v[110:113]
	v_mfma_f32_16x16x32_bf16 v[110:113], v[146:149], v[192:195], v[110:113]
	v_mfma_f32_16x16x32_bf16 v[94:97], v[146:149], v[200:203], v[94:97]
	v_mfma_f32_16x16x32_bf16 v[94:97], v[156:159], v[204:207], v[94:97]
	v_mfma_f32_16x16x32_bf16 v[90:93], v[164:167], v[204:207], v[90:93]
	v_mfma_f32_16x16x32_bf16 v[90:93], v[160:163], v[200:203], v[90:93]
	v_mfma_f32_16x16x32_bf16 v[74:77], v[160:163], v[208:211], v[74:77]
	v_mfma_f32_16x16x32_bf16 v[74:77], v[164:167], v[212:215], v[74:77]
	v_mfma_f32_16x16x32_bf16 v[78:81], v[156:159], v[212:215], v[78:81]
	v_mfma_f32_16x16x32_bf16 v[78:81], v[146:149], v[208:211], v[78:81]
	s_setprio 0
	s_setprio 1
	v_mfma_f32_16x16x32_bf16 v[118:121], v[168:171], v[184:187], v[118:121]
	v_mfma_f32_16x16x32_bf16 v[118:121], v[172:175], v[188:191], v[118:121]
	v_mfma_f32_16x16x32_bf16 v[114:117], v[180:183], v[188:191], v[114:117]
	v_mfma_f32_16x16x32_bf16 v[114:117], v[176:179], v[184:187], v[114:117]
	v_mfma_f32_16x16x32_bf16 v[98:101], v[176:179], v[192:195], v[98:101]
	v_mfma_f32_16x16x32_bf16 v[98:101], v[180:183], v[196:199], v[98:101]
	v_mfma_f32_16x16x32_bf16 v[102:105], v[172:175], v[196:199], v[102:105]
	v_mfma_f32_16x16x32_bf16 v[102:105], v[168:171], v[192:195], v[102:105]
	v_mfma_f32_16x16x32_bf16 v[86:89], v[168:171], v[200:203], v[86:89]
	v_mfma_f32_16x16x32_bf16 v[86:89], v[172:175], v[204:207], v[86:89]
	v_mfma_f32_16x16x32_bf16 v[82:85], v[180:183], v[204:207], v[82:85]
	v_mfma_f32_16x16x32_bf16 v[82:85], v[176:179], v[200:203], v[82:85]
	v_mfma_f32_16x16x32_bf16 v[66:69], v[176:179], v[208:211], v[66:69]
	v_mfma_f32_16x16x32_bf16 v[66:69], v[180:183], v[212:215], v[66:69]
	v_mfma_f32_16x16x32_bf16 v[70:73], v[172:175], v[212:215], v[70:73]
	v_mfma_f32_16x16x32_bf16 v[70:73], v[168:171], v[208:211], v[70:73]
	s_setprio 0
	s_barrier
	s_add_i32 s14, s35, s2
	v_lshl_add_u64 v[216:217], s[18:19], 0, v[134:135]
	s_mov_b32 m0, s14
	ds_read_b128 v[184:187], v154 offset:16384
	ds_read_b128 v[188:191], v154 offset:17408
	ds_read_b128 v[192:195], v154 offset:18432
	ds_read_b128 v[196:199], v154 offset:19456
	ds_read_b128 v[200:203], v154 offset:20480
	ds_read_b128 v[204:207], v154 offset:21504
	ds_read_b128 v[208:211], v154 offset:22528
	ds_read_b128 v[212:215], v154 offset:23552
	global_load_lds_dwordx4 v[216:217], off
	s_add_i32 m0, s14, 0x2000
	s_add_u32 s14, s18, 0x108000
	v_lshl_add_u64 v[218:219], s[18:19], 0, v[130:131]
	s_addc_u32 s15, s19, 0
	s_add_i32 s45, s36, s2
	global_load_lds_dwordx4 v[218:219], off
	v_lshl_add_u64 v[220:221], s[14:15], 0, v[134:135]
	s_mov_b32 m0, s45
	v_lshl_add_u64 v[222:223], s[20:21], 0, v[132:133]
	global_load_lds_dwordx4 v[220:221], off
	v_lshl_add_u64 v[220:221], s[14:15], 0, v[130:131]
	s_add_i32 m0, s45, 0x2000
	s_nop 0
	global_load_lds_dwordx4 v[220:221], off
	v_lshl_add_u64 v[220:221], s[20:21], 0, v[136:137]
	s_mov_b32 m0, s26
	s_nop 0
	global_load_lds_dwordx4 v[220:221], off
	s_mov_b32 m0, s27
	s_nop 0
	global_load_lds_dwordx4 v[222:223], off
	s_waitcnt vmcnt(8)
	s_waitcnt lgkmcnt(0)
	s_barrier
; #define PG8_STAGE(bufoff, gbase, voff) do { _Pragma("unroll") for (int _i = 0; _i < 2; ++_i) \
;         __builtin_amdgcn_global_load_lds((const unsigned*)((const char*)(gbase) + (voff)[_i]), (PG8_LAS unsigned*)(lds + (bufoff) + ldsw + _i * 8192), 16, 0, 0); } while (0)
; #define PG8_LDA(dst, b, h) do { _Pragma("unroll") for (int m = 0; m < 4; ++m) _Pragma("unroll") for (int k = 0; k < 2; ++k) dst[m][k] = *(const PG8_LAS bf16x8*)(lds + PG8_SA(b, h) + aoff + m * 2048 + k * 1024); } while (0)
; #define PG8_LDB(dst, b, h) do { _Pragma("unroll") for (int n = 0; n < 2; ++n) _Pragma("unroll") for (int k = 0; k < 2; ++k) dst[n][k] = *(const PG8_LAS bf16x8*)(lds + PG8_SB(b, h) + boff + n * 2048 + k * 1024); } while (0)
; #define PG8_MMA(ai, bj, At, Bt) do { __builtin_amdgcn_s_setprio(1); _Pragma("unroll") for (int m = 0; m < 4; ++m) _Pragma("unroll") for (int n = 0; n < 2; ++n) _Pragma("unroll") for (int k = 0; k < 2; ++k) \
;         acc[ai][bj][m][n] = __builtin_amdgcn_mfma_f32_16x16x32_bf16(Bt[n][k], At[m][k], acc[ai][bj][m][n], 0, 0, 0); __builtin_amdgcn_s_setprio(0); } while (0)
; #define PG8_WAIT_V(n) asm volatile("s_waitcnt vmcnt(" #n ")" ::: "memory")
; #define PG8_WAIT_L(n) asm volatile("s_waitcnt lgkmcnt(" #n ")" ::: "memory")
; #define PG8_BAR __builtin_amdgcn_s_barrier()
; #define PG8_SCHED __builtin_amdgcn_sched_barrier(0)
; template <class Epi, class Sched, bool ALIGN_EPI = false, bool SP2 = false>
; __device__ __forceinline__ void gemm_phase(PG8_LAS unsigned char* lds, const Gemm g, const Sched& S, const Epi& E) {
;     ...
;             PG8_WAIT_V(8); PG8_WAIT_L(0); PG8_BAR; PG8_MMA(1, 0, At, B0); PG8_MMA(1, 1, At, B1); PG8_BAR; PG8_SCHED;
;             PG8_LDB(B0, 1, 0); PG8_LDB(B1, 1, 1); PG8_SCHED; PG8_LDA(At, 1, 0); PG8_STAGE(PG8_SA(0, 1), a2 + hstep, voffA);
;             PG8_WAIT_V(8); PG8_WAIT_L(0); PG8_BAR; PG8_MMA(0, 0, At, B0); PG8_MMA(0, 1, At, B1); PG8_BAR; PG8_SCHED;
	s_setprio 1
	s_waitcnt lgkmcnt(0)
	v_mfma_f32_16x16x32_bf16 v[62:65], v[146:149], v[184:187], v[62:65]
	v_mfma_f32_16x16x32_bf16 v[62:65], v[156:159], v[188:191], v[62:65]
	v_mfma_f32_16x16x32_bf16 v[58:61], v[164:167], v[188:191], v[58:61]
	v_mfma_f32_16x16x32_bf16 v[58:61], v[160:163], v[184:187], v[58:61]
	v_mfma_f32_16x16x32_bf16 v[42:45], v[160:163], v[192:195], v[42:45]
	v_mfma_f32_16x16x32_bf16 v[42:45], v[164:167], v[196:199], v[42:45]
	v_mfma_f32_16x16x32_bf16 v[46:49], v[156:159], v[196:199], v[46:49]
	v_mfma_f32_16x16x32_bf16 v[46:49], v[146:149], v[192:195], v[46:49]
	v_mfma_f32_16x16x32_bf16 v[30:33], v[146:149], v[200:203], v[30:33]
	v_mfma_f32_16x16x32_bf16 v[30:33], v[156:159], v[204:207], v[30:33]
	v_mfma_f32_16x16x32_bf16 v[26:29], v[164:167], v[204:207], v[26:29]
	v_mfma_f32_16x16x32_bf16 v[26:29], v[160:163], v[200:203], v[26:29]
	v_mfma_f32_16x16x32_bf16 v[10:13], v[160:163], v[208:211], v[10:13]
	v_mfma_f32_16x16x32_bf16 v[10:13], v[164:167], v[212:215], v[10:13]
	v_mfma_f32_16x16x32_bf16 v[14:17], v[156:159], v[212:215], v[14:17]
	v_mfma_f32_16x16x32_bf16 v[14:17], v[146:149], v[208:211], v[14:17]
	s_setprio 0
	s_setprio 1
	v_mfma_f32_16x16x32_bf16 v[54:57], v[168:171], v[184:187], v[54:57]
	v_mfma_f32_16x16x32_bf16 v[54:57], v[172:175], v[188:191], v[54:57]
	v_mfma_f32_16x16x32_bf16 v[50:53], v[180:183], v[188:191], v[50:53]
	v_mfma_f32_16x16x32_bf16 v[50:53], v[176:179], v[184:187], v[50:53]
	v_mfma_f32_16x16x32_bf16 v[34:37], v[176:179], v[192:195], v[34:37]
	v_mfma_f32_16x16x32_bf16 v[34:37], v[180:183], v[196:199], v[34:37]
	v_mfma_f32_16x16x32_bf16 v[38:41], v[172:175], v[196:199], v[38:41]
	v_mfma_f32_16x16x32_bf16 v[38:41], v[168:171], v[192:195], v[38:41]
	v_mfma_f32_16x16x32_bf16 v[22:25], v[168:171], v[200:203], v[22:25]
	v_mfma_f32_16x16x32_bf16 v[22:25], v[172:175], v[204:207], v[22:25]
	v_mfma_f32_16x16x32_bf16 v[18:21], v[180:183], v[204:207], v[18:21]
	v_mfma_f32_16x16x32_bf16 v[18:21], v[176:179], v[200:203], v[18:21]
	v_mfma_f32_16x16x32_bf16 v[2:5], v[176:179], v[208:211], v[2:5]
	v_mfma_f32_16x16x32_bf16 v[2:5], v[180:183], v[212:215], v[2:5]
	v_mfma_f32_16x16x32_bf16 v[6:9], v[172:175], v[212:215], v[6:9]
	v_mfma_f32_16x16x32_bf16 v[6:9], v[168:171], v[208:211], v[6:9]
	s_setprio 0
	s_barrier
	s_add_i32 s45, 0, 0x18000
	v_add_u32_e32 v155, s45, v150
	s_add_i32 s46, 0, 0x1c000
	ds_read_b128 v[146:149], v155
	ds_read_b128 v[156:159], v155 offset:1024
	ds_read_b128 v[160:163], v155 offset:2048
	ds_read_b128 v[164:167], v155 offset:3072
	v_add_u32_e32 v155, s46, v150
	ds_read_b128 v[168:171], v155
	ds_read_b128 v[172:175], v155 offset:1024
	ds_read_b128 v[176:179], v155 offset:2048
	ds_read_b128 v[180:183], v155 offset:3072
	s_add_u32 s14, s20, 0x108000
	s_addc_u32 s15, s21, 0
	s_mov_b32 m0, s28
	v_lshl_add_u64 v[224:225], s[14:15], 0, v[136:137]
	ds_read_b128 v[184:187], v154 offset:32768
	ds_read_b128 v[188:191], v154 offset:33792
	ds_read_b128 v[192:195], v154 offset:34816
	ds_read_b128 v[196:199], v154 offset:35840
	ds_read_b128 v[200:203], v154 offset:36864
	ds_read_b128 v[204:207], v154 offset:37888
	ds_read_b128 v[208:211], v154 offset:38912
	ds_read_b128 v[212:215], v154 offset:39936
	global_load_lds_dwordx4 v[224:225], off
	v_lshl_add_u64 v[224:225], s[14:15], 0, v[132:133]
	s_mov_b32 m0, s29
	s_nop 0
	global_load_lds_dwordx4 v[224:225], off
	s_waitcnt vmcnt(8)
	s_waitcnt lgkmcnt(0)
	s_barrier
	s_setprio 1
	s_waitcnt lgkmcnt(0)
	v_mfma_f32_16x16x32_bf16 v[126:129], v[146:149], v[184:187], v[126:129]
	v_mfma_f32_16x16x32_bf16 v[126:129], v[156:159], v[188:191], v[126:129]
	v_mfma_f32_16x16x32_bf16 v[122:125], v[164:167], v[188:191], v[122:125]
	v_mfma_f32_16x16x32_bf16 v[122:125], v[160:163], v[184:187], v[122:125]
	v_mfma_f32_16x16x32_bf16 v[106:109], v[160:163], v[192:195], v[106:109]
	v_mfma_f32_16x16x32_bf16 v[106:109], v[164:167], v[196:199], v[106:109]
	v_mfma_f32_16x16x32_bf16 v[110:113], v[156:159], v[196:199], v[110:113]
	v_mfma_f32_16x16x32_bf16 v[110:113], v[146:149], v[192:195], v[110:113]
	v_mfma_f32_16x16x32_bf16 v[94:97], v[146:149], v[200:203], v[94:97]
	v_mfma_f32_16x16x32_bf16 v[94:97], v[156:159], v[204:207], v[94:97]
	v_mfma_f32_16x16x32_bf16 v[90:93], v[164:167], v[204:207], v[90:93]
	v_mfma_f32_16x16x32_bf16 v[90:93], v[160:163], v[200:203], v[90:93]
	v_mfma_f32_16x16x32_bf16 v[74:77], v[160:163], v[208:211], v[74:77]
	v_mfma_f32_16x16x32_bf16 v[74:77], v[164:167], v[212:215], v[74:77]
	v_mfma_f32_16x16x32_bf16 v[78:81], v[156:159], v[212:215], v[78:81]
	v_mfma_f32_16x16x32_bf16 v[78:81], v[146:149], v[208:211], v[78:81]
	s_setprio 0
	s_setprio 1
	v_mfma_f32_16x16x32_bf16 v[118:121], v[168:171], v[184:187], v[118:121]
	v_mfma_f32_16x16x32_bf16 v[118:121], v[172:175], v[188:191], v[118:121]
	v_mfma_f32_16x16x32_bf16 v[114:117], v[180:183], v[188:191], v[114:117]
	v_mfma_f32_16x16x32_bf16 v[114:117], v[176:179], v[184:187], v[114:117]
	v_mfma_f32_16x16x32_bf16 v[98:101], v[176:179], v[192:195], v[98:101]
	v_mfma_f32_16x16x32_bf16 v[98:101], v[180:183], v[196:199], v[98:101]
	v_mfma_f32_16x16x32_bf16 v[102:105], v[172:175], v[196:199], v[102:105]
	v_mfma_f32_16x16x32_bf16 v[102:105], v[168:171], v[192:195], v[102:105]
	v_mfma_f32_16x16x32_bf16 v[86:89], v[168:171], v[200:203], v[86:89]
	v_mfma_f32_16x16x32_bf16 v[86:89], v[172:175], v[204:207], v[86:89]
	v_mfma_f32_16x16x32_bf16 v[82:85], v[180:183], v[204:207], v[82:85]
	v_mfma_f32_16x16x32_bf16 v[82:85], v[176:179], v[200:203], v[82:85]
	v_mfma_f32_16x16x32_bf16 v[66:69], v[176:179], v[208:211], v[66:69]
	v_mfma_f32_16x16x32_bf16 v[66:69], v[180:183], v[212:215], v[66:69]
	v_mfma_f32_16x16x32_bf16 v[70:73], v[172:175], v[212:215], v[70:73]
	v_mfma_f32_16x16x32_bf16 v[70:73], v[168:171], v[208:211], v[70:73]
	s_setprio 0
	s_barrier
; #define PG8_STAGE(bufoff, gbase, voff) do { _Pragma("unroll") for (int _i = 0; _i < 2; ++_i) \
;         __builtin_amdgcn_global_load_lds((const unsigned*)((const char*)(gbase) + (voff)[_i]), (PG8_LAS unsigned*)(lds + (bufoff) + ldsw + _i * 8192), 16, 0, 0); } while (0)
; #define PG8_LDA(dst, b, h) do { _Pragma("unroll") for (int m = 0; m < 4; ++m) _Pragma("unroll") for (int k = 0; k < 2; ++k) dst[m][k] = *(const PG8_LAS bf16x8*)(lds + PG8_SA(b, h) + aoff + m * 2048 + k * 1024); } while (0)
; #define PG8_MMA(ai, bj, At, Bt) do { __builtin_amdgcn_s_setprio(1); _Pragma("unroll") for (int m = 0; m < 4; ++m) _Pragma("unroll") for (int n = 0; n < 2; ++n) _Pragma("unroll") for (int k = 0; k < 2; ++k) \
;         acc[ai][bj][m][n] = __builtin_amdgcn_mfma_f32_16x16x32_bf16(Bt[n][k], At[m][k], acc[ai][bj][m][n], 0, 0, 0); __builtin_amdgcn_s_setprio(0); } while (0)
; #define PG8_WAIT_V(n) asm volatile("s_waitcnt vmcnt(" #n ")" ::: "memory")
; #define PG8_WAIT_L(n) asm volatile("s_waitcnt lgkmcnt(" #n ")" ::: "memory")
; #define PG8_BAR __builtin_amdgcn_s_barrier()
; #define PG8_SCHED __builtin_amdgcn_sched_barrier(0)
; template <class Epi, class Sched, bool ALIGN_EPI = false, bool SP2 = false>
; __device__ __forceinline__ void gemm_phase(PG8_LAS unsigned char* lds, const Gemm g, const Sched& S, const Epi& E) {
;     ...
;             PG8_LDA(At, 1, 1); PG8_STAGE(PG8_SB(1, 0), b3, voffB); PG8_STAGE(PG8_SB(1, 1), b3 + hstepB, voffB); PG8_STAGE(PG8_SA(1, 0), a3, voffA);
;             PG8_WAIT_V(8); PG8_WAIT_L(0); PG8_BAR; PG8_MMA(1, 0, At, B0); PG8_MMA(1, 1, At, B1); PG8_BAR; PG8_SCHED;
	s_add_i32 s14, s45, s2
	v_lshl_add_u64 v[216:217], v[216:217], 0, s[8:9]
	s_mov_b32 m0, s14
	ds_read_b128 v[184:187], v154 offset:49152
	ds_read_b128 v[188:191], v154 offset:50176
	ds_read_b128 v[192:195], v154 offset:51200
	ds_read_b128 v[196:199], v154 offset:52224
	ds_read_b128 v[200:203], v154 offset:53248
	ds_read_b128 v[204:207], v154 offset:54272
	ds_read_b128 v[208:211], v154 offset:55296
	ds_read_b128 v[212:215], v154 offset:56320
	global_load_lds_dwordx4 v[216:217], off
	s_add_i32 m0, s14, 0x2000
	s_add_u32 s14, s18, 0x108080
	v_lshl_add_u64 v[216:217], v[218:219], 0, s[8:9]
	s_addc_u32 s15, s19, 0
	s_add_i32 s18, s46, s2
	global_load_lds_dwordx4 v[216:217], off
	v_lshl_add_u64 v[216:217], s[14:15], 0, v[134:135]
	s_mov_b32 m0, s18
	s_nop 0
	global_load_lds_dwordx4 v[216:217], off
	v_lshl_add_u64 v[216:217], s[14:15], 0, v[130:131]
	s_add_i32 m0, s18, 0x2000
	s_nop 0
	global_load_lds_dwordx4 v[216:217], off
	v_lshl_add_u64 v[216:217], v[220:221], 0, s[8:9]
	s_mov_b32 m0, s31
	s_nop 0
	global_load_lds_dwordx4 v[216:217], off
	v_lshl_add_u64 v[216:217], v[222:223], 0, s[8:9]
	s_mov_b32 m0, s33
	s_nop 0
	global_load_lds_dwordx4 v[216:217], off
	s_waitcnt vmcnt(8)
	s_waitcnt lgkmcnt(0)
	s_barrier
	s_setprio 1
	s_waitcnt lgkmcnt(0)
	v_mfma_f32_16x16x32_bf16 v[62:65], v[146:149], v[184:187], v[62:65]
	v_mfma_f32_16x16x32_bf16 v[62:65], v[156:159], v[188:191], v[62:65]
	v_mfma_f32_16x16x32_bf16 v[58:61], v[164:167], v[188:191], v[58:61]
	v_mfma_f32_16x16x32_bf16 v[58:61], v[160:163], v[184:187], v[58:61]
	v_mfma_f32_16x16x32_bf16 v[42:45], v[160:163], v[192:195], v[42:45]
	v_mfma_f32_16x16x32_bf16 v[42:45], v[164:167], v[196:199], v[42:45]
	v_mfma_f32_16x16x32_bf16 v[46:49], v[156:159], v[196:199], v[46:49]
	v_mfma_f32_16x16x32_bf16 v[46:49], v[146:149], v[192:195], v[46:49]
	v_mfma_f32_16x16x32_bf16 v[30:33], v[146:149], v[200:203], v[30:33]
	v_mfma_f32_16x16x32_bf16 v[30:33], v[156:159], v[204:207], v[30:33]
	v_mfma_f32_16x16x32_bf16 v[26:29], v[164:167], v[204:207], v[26:29]
	v_mfma_f32_16x16x32_bf16 v[26:29], v[160:163], v[200:203], v[26:29]
	v_mfma_f32_16x16x32_bf16 v[10:13], v[160:163], v[208:211], v[10:13]
	v_mfma_f32_16x16x32_bf16 v[10:13], v[164:167], v[212:215], v[10:13]
	v_mfma_f32_16x16x32_bf16 v[14:17], v[156:159], v[212:215], v[14:17]
	v_mfma_f32_16x16x32_bf16 v[14:17], v[146:149], v[208:211], v[14:17]
	s_setprio 0
	s_setprio 1
	v_mfma_f32_16x16x32_bf16 v[54:57], v[168:171], v[184:187], v[54:57]
	v_mfma_f32_16x16x32_bf16 v[54:57], v[172:175], v[188:191], v[54:57]
	v_mfma_f32_16x16x32_bf16 v[50:53], v[180:183], v[188:191], v[50:53]
	v_mfma_f32_16x16x32_bf16 v[50:53], v[176:179], v[184:187], v[50:53]
	v_mfma_f32_16x16x32_bf16 v[34:37], v[176:179], v[192:195], v[34:37]
	v_mfma_f32_16x16x32_bf16 v[34:37], v[180:183], v[196:199], v[34:37]
	v_mfma_f32_16x16x32_bf16 v[38:41], v[172:175], v[196:199], v[38:41]
	v_mfma_f32_16x16x32_bf16 v[38:41], v[168:171], v[192:195], v[38:41]
	v_mfma_f32_16x16x32_bf16 v[22:25], v[168:171], v[200:203], v[22:25]
	v_mfma_f32_16x16x32_bf16 v[22:25], v[172:175], v[204:207], v[22:25]
	v_mfma_f32_16x16x32_bf16 v[18:21], v[180:183], v[204:207], v[18:21]
	v_mfma_f32_16x16x32_bf16 v[18:21], v[176:179], v[200:203], v[18:21]
	v_mfma_f32_16x16x32_bf16 v[2:5], v[176:179], v[208:211], v[2:5]
	v_mfma_f32_16x16x32_bf16 v[2:5], v[180:183], v[212:215], v[2:5]
	v_mfma_f32_16x16x32_bf16 v[6:9], v[172:175], v[212:215], v[6:9]
	v_mfma_f32_16x16x32_bf16 v[6:9], v[168:171], v[208:211], v[6:9]
	s_setprio 0
	s_barrier
	s_add_i32 s44, s44, 2
	s_add_u32 s42, s42, 0x100
	s_addc_u32 s43, s43, 0
	s_cmp_gt_u32 s44, 61
	s_mov_b64 s[14:15], s[16:17]
	s_cbranch_scc0 .LBB0_1889
	s_and_b64 vcc, exec, s[10:11]
	s_cbranch_vccz .LBB0_1892
	s_barrier

; #define PG8_STAGE(bufoff, gbase, voff) do { _Pragma("unroll") for (int _i = 0; _i < 2; ++_i) \
;         __builtin_amdgcn_global_load_lds((const unsigned*)((const char*)(gbase) + (voff)[_i]), (PG8_LAS unsigned*)(lds + (bufoff) + ldsw + _i * 8192), 16, 0, 0); } while (0)
; #define PG8_LDA(dst, b, h) do { _Pragma("unroll") for (int m = 0; m < 4; ++m) _Pragma("unroll") for (int k = 0; k < 2; ++k) dst[m][k] = *(const PG8_LAS bf16x8*)(lds + PG8_SA(b, h) + aoff + m * 2048 + k * 1024); } while (0)
; #define PG8_LDB(dst, b, h) do { _Pragma("unroll") for (int n = 0; n < 2; ++n) _Pragma("unroll") for (int k = 0; k < 2; ++k) dst[n][k] = *(const PG8_LAS bf16x8*)(lds + PG8_SB(b, h) + boff + n * 2048 + k * 1024); } while (0)
; #define PG8_MMA(ai, bj, At, Bt) do { __builtin_amdgcn_s_setprio(1); _Pragma("unroll") for (int m = 0; m < 4; ++m) _Pragma("unroll") for (int n = 0; n < 2; ++n) _Pragma("unroll") for (int k = 0; k < 2; ++k) \
;         acc[ai][bj][m][n] = __builtin_amdgcn_mfma_f32_16x16x32_bf16(Bt[n][k], At[m][k], acc[ai][bj][m][n], 0, 0, 0); __builtin_amdgcn_s_setprio(0); } while (0)
; #define PG8_WAIT_V(n) asm volatile("s_waitcnt vmcnt(" #n ")" ::: "memory")
; #define PG8_WAIT_L(n) asm volatile("s_waitcnt lgkmcnt(" #n ")" ::: "memory")
; #define PG8_BAR __builtin_amdgcn_s_barrier()
; #define PG8_SCHED __builtin_amdgcn_sched_barrier(0)
; template <class Epi, class Sched, bool ALIGN_EPI = false, bool SP2 = false>
; __device__ __forceinline__ void gemm_phase(PG8_LAS unsigned char* lds, const Gemm g, const Sched& S, const Epi& E) {
;     ...
;             PG8_LDB(B0, 0, 0); PG8_LDB(B1, 0, 1); PG8_SCHED; PG8_LDA(At, 0, 0); PG8_STAGE(PG8_SA(1, 1), a1 + hstep, voffA);
;             PG8_WAIT_V(8); PG8_WAIT_L(0); PG8_BAR; PG8_MMA(0, 0, At, B0); PG8_MMA(0, 1, At, B1); PG8_BAR; PG8_SCHED;
;             PG8_LDA(At, 0, 1); PG8_STAGE(PG8_SB(0, 0), b2, voffB); PG8_STAGE(PG8_SB(0, 1), b2 + hstepB, voffB); PG8_STAGE(PG8_SA(0, 0), a2, voffA);
;             PG8_WAIT_V(8); PG8_WAIT_L(0); PG8_BAR; PG8_MMA(1, 0, At, B0); PG8_MMA(1, 1, At, B1); PG8_BAR; PG8_SCHED;
.LBB0_2165:
	ds_read_b128 v[128:131], v167
	ds_read_b128 v[132:135], v167 offset:1024
	ds_read_b128 v[136:139], v167 offset:2048
	ds_read_b128 v[140:143], v167 offset:3072
	ds_read_b128 v[160:163], v168
	ds_read_b128 v[170:173], v168 offset:1024
	ds_read_b128 v[174:177], v168 offset:2048
	ds_read_b128 v[178:181], v168 offset:3072
	s_add_u32 s16, s14, 0x100
	s_addc_u32 s17, s15, 0
	s_cmpk_eq_i32 s57, 0xa8
	s_cselect_b32 s21, s5, s17
	s_cselect_b32 s20, s4, s16
	s_cselect_b32 s19, s13, s56
	s_cselect_b32 s18, s12, s55
	v_lshl_add_u64 v[214:215], s[14:15], 0, v[152:153]
	s_add_i32 m0, s25, 0xc000
	ds_read_b128 v[182:185], v169
	ds_read_b128 v[186:189], v169 offset:1024
	ds_read_b128 v[190:193], v169 offset:2048
	ds_read_b128 v[194:197], v169 offset:3072
	ds_read_b128 v[198:201], v169 offset:4096
	ds_read_b128 v[202:205], v169 offset:5120
	ds_read_b128 v[206:209], v169 offset:6144
	ds_read_b128 v[210:213], v169 offset:7168
	global_load_lds_dwordx4 v[214:215], off
	v_lshl_add_u64 v[214:215], s[14:15], 0, v[154:155]
	s_add_i32 m0, s25, 0xe000
	s_nop 0
	global_load_lds_dwordx4 v[214:215], off
	s_waitcnt vmcnt(8)
	s_waitcnt lgkmcnt(0)
	s_barrier
	s_setprio 1
	s_waitcnt lgkmcnt(0)
	v_mfma_f32_16x16x32_bf16 v[124:127], v[128:131], v[182:185], v[124:127]
	v_mfma_f32_16x16x32_bf16 v[124:127], v[132:135], v[186:189], v[124:127]
	v_mfma_f32_16x16x32_bf16 v[120:123], v[140:143], v[186:189], v[120:123]
	v_mfma_f32_16x16x32_bf16 v[120:123], v[136:139], v[182:185], v[120:123]
	v_mfma_f32_16x16x32_bf16 v[108:111], v[136:139], v[190:193], v[108:111]
	v_mfma_f32_16x16x32_bf16 v[108:111], v[140:143], v[194:197], v[108:111]
	v_mfma_f32_16x16x32_bf16 v[116:119], v[132:135], v[194:197], v[116:119]
	v_mfma_f32_16x16x32_bf16 v[116:119], v[128:131], v[190:193], v[116:119]
	v_mfma_f32_16x16x32_bf16 v[92:95], v[128:131], v[198:201], v[92:95]
	v_mfma_f32_16x16x32_bf16 v[92:95], v[132:135], v[202:205], v[92:95]
	v_mfma_f32_16x16x32_bf16 v[88:91], v[140:143], v[202:205], v[88:91]
	v_mfma_f32_16x16x32_bf16 v[88:91], v[136:139], v[198:201], v[88:91]
	v_mfma_f32_16x16x32_bf16 v[72:75], v[136:139], v[206:209], v[72:75]
	v_mfma_f32_16x16x32_bf16 v[72:75], v[140:143], v[210:213], v[72:75]
	v_mfma_f32_16x16x32_bf16 v[80:83], v[132:135], v[210:213], v[80:83]
	v_mfma_f32_16x16x32_bf16 v[80:83], v[128:131], v[206:209], v[80:83]
	s_setprio 0
	s_setprio 1
	v_mfma_f32_16x16x32_bf16 v[112:115], v[160:163], v[182:185], v[112:115]
	v_mfma_f32_16x16x32_bf16 v[112:115], v[170:173], v[186:189], v[112:115]
	v_mfma_f32_16x16x32_bf16 v[104:107], v[178:181], v[186:189], v[104:107]
	v_mfma_f32_16x16x32_bf16 v[104:107], v[174:177], v[182:185], v[104:107]
	v_mfma_f32_16x16x32_bf16 v[96:99], v[174:177], v[190:193], v[96:99]
	v_mfma_f32_16x16x32_bf16 v[96:99], v[178:181], v[194:197], v[96:99]
	v_mfma_f32_16x16x32_bf16 v[100:103], v[170:173], v[194:197], v[100:103]
	v_mfma_f32_16x16x32_bf16 v[100:103], v[160:163], v[190:193], v[100:103]
	v_mfma_f32_16x16x32_bf16 v[84:87], v[160:163], v[198:201], v[84:87]
	v_mfma_f32_16x16x32_bf16 v[84:87], v[170:173], v[202:205], v[84:87]
	v_mfma_f32_16x16x32_bf16 v[76:79], v[178:181], v[202:205], v[76:79]
	v_mfma_f32_16x16x32_bf16 v[76:79], v[174:177], v[198:201], v[76:79]
	v_mfma_f32_16x16x32_bf16 v[64:67], v[174:177], v[206:209], v[64:67]
	v_mfma_f32_16x16x32_bf16 v[64:67], v[178:181], v[210:213], v[64:67]
	v_mfma_f32_16x16x32_bf16 v[68:71], v[170:173], v[210:213], v[68:71]
	v_mfma_f32_16x16x32_bf16 v[68:71], v[160:163], v[206:209], v[68:71]
	s_setprio 0
	s_barrier
	s_add_i32 s14, s36, s24
	v_lshl_add_u64 v[214:215], s[18:19], 0, v[146:147]
	s_mov_b32 m0, s14
	ds_read_b128 v[182:185], v169 offset:16384
	ds_read_b128 v[186:189], v169 offset:17408
	ds_read_b128 v[190:193], v169 offset:18432
	ds_read_b128 v[194:197], v169 offset:19456
	ds_read_b128 v[198:201], v169 offset:20480
	ds_read_b128 v[202:205], v169 offset:21504
	ds_read_b128 v[206:209], v169 offset:22528
	ds_read_b128 v[210:213], v169 offset:23552
	global_load_lds_dwordx4 v[214:215], off
	s_add_i32 m0, s14, 0x2000
	s_add_u32 s14, s18, 0x2b0000
	v_lshl_add_u64 v[216:217], s[18:19], 0, v[150:151]
	s_addc_u32 s15, s19, 0
	s_add_i32 s58, s37, s24
	global_load_lds_dwordx4 v[216:217], off
	v_lshl_add_u64 v[218:219], s[14:15], 0, v[146:147]
	s_mov_b32 m0, s58
	v_lshl_add_u64 v[220:221], s[20:21], 0, v[148:149]
	global_load_lds_dwordx4 v[218:219], off
	v_lshl_add_u64 v[218:219], s[14:15], 0, v[150:151]
	s_add_i32 m0, s58, 0x2000
	s_nop 0
	global_load_lds_dwordx4 v[218:219], off
	v_lshl_add_u64 v[218:219], s[20:21], 0, v[144:145]
	s_mov_b32 m0, s25
	s_nop 0
	global_load_lds_dwordx4 v[218:219], off
	s_mov_b32 m0, s26
	s_nop 0
	global_load_lds_dwordx4 v[220:221], off
	s_waitcnt vmcnt(8)
	s_waitcnt lgkmcnt(0)
	s_barrier
; #define PG8_STAGE(bufoff, gbase, voff) do { _Pragma("unroll") for (int _i = 0; _i < 2; ++_i) \
;         __builtin_amdgcn_global_load_lds((const unsigned*)((const char*)(gbase) + (voff)[_i]), (PG8_LAS unsigned*)(lds + (bufoff) + ldsw + _i * 8192), 16, 0, 0); } while (0)
; #define PG8_LDA(dst, b, h) do { _Pragma("unroll") for (int m = 0; m < 4; ++m) _Pragma("unroll") for (int k = 0; k < 2; ++k) dst[m][k] = *(const PG8_LAS bf16x8*)(lds + PG8_SA(b, h) + aoff + m * 2048 + k * 1024); } while (0)
; #define PG8_LDB(dst, b, h) do { _Pragma("unroll") for (int n = 0; n < 2; ++n) _Pragma("unroll") for (int k = 0; k < 2; ++k) dst[n][k] = *(const PG8_LAS bf16x8*)(lds + PG8_SB(b, h) + boff + n * 2048 + k * 1024); } while (0)
; #define PG8_MMA(ai, bj, At, Bt) do { __builtin_amdgcn_s_setprio(1); _Pragma("unroll") for (int m = 0; m < 4; ++m) _Pragma("unroll") for (int n = 0; n < 2; ++n) _Pragma("unroll") for (int k = 0; k < 2; ++k) \
;         acc[ai][bj][m][n] = __builtin_amdgcn_mfma_f32_16x16x32_bf16(Bt[n][k], At[m][k], acc[ai][bj][m][n], 0, 0, 0); __builtin_amdgcn_s_setprio(0); } while (0)
; #define PG8_WAIT_V(n) asm volatile("s_waitcnt vmcnt(" #n ")" ::: "memory")
; #define PG8_WAIT_L(n) asm volatile("s_waitcnt lgkmcnt(" #n ")" ::: "memory")
; #define PG8_BAR __builtin_amdgcn_s_barrier()
; #define PG8_SCHED __builtin_amdgcn_sched_barrier(0)
; template <class Epi, class Sched, bool ALIGN_EPI = false, bool SP2 = false>
; __device__ __forceinline__ void gemm_phase(PG8_LAS unsigned char* lds, const Gemm g, const Sched& S, const Epi& E) {
;     ...
;             PG8_WAIT_V(8); PG8_WAIT_L(0); PG8_BAR; PG8_MMA(1, 0, At, B0); PG8_MMA(1, 1, At, B1); PG8_BAR; PG8_SCHED;
;             PG8_LDB(B0, 1, 0); PG8_LDB(B1, 1, 1); PG8_SCHED; PG8_LDA(At, 1, 0); PG8_STAGE(PG8_SA(0, 1), a2 + hstep, voffA);
;             PG8_WAIT_V(8); PG8_WAIT_L(0); PG8_BAR; PG8_MMA(0, 0, At, B0); PG8_MMA(0, 1, At, B1); PG8_BAR; PG8_SCHED;
	s_setprio 1
	s_waitcnt lgkmcnt(0)
	v_mfma_f32_16x16x32_bf16 v[60:63], v[128:131], v[182:185], v[60:63]
	v_mfma_f32_16x16x32_bf16 v[60:63], v[132:135], v[186:189], v[60:63]
	v_mfma_f32_16x16x32_bf16 v[56:59], v[140:143], v[186:189], v[56:59]
	v_mfma_f32_16x16x32_bf16 v[56:59], v[136:139], v[182:185], v[56:59]
	v_mfma_f32_16x16x32_bf16 v[40:43], v[136:139], v[190:193], v[40:43]
	v_mfma_f32_16x16x32_bf16 v[40:43], v[140:143], v[194:197], v[40:43]
	v_mfma_f32_16x16x32_bf16 v[48:51], v[132:135], v[194:197], v[48:51]
	v_mfma_f32_16x16x32_bf16 v[48:51], v[128:131], v[190:193], v[48:51]
	v_mfma_f32_16x16x32_bf16 v[28:31], v[128:131], v[198:201], v[28:31]
	v_mfma_f32_16x16x32_bf16 v[28:31], v[132:135], v[202:205], v[28:31]
	v_mfma_f32_16x16x32_bf16 v[24:27], v[140:143], v[202:205], v[24:27]
	v_mfma_f32_16x16x32_bf16 v[24:27], v[136:139], v[198:201], v[24:27]
	v_mfma_f32_16x16x32_bf16 v[12:15], v[136:139], v[206:209], v[12:15]
	v_mfma_f32_16x16x32_bf16 v[12:15], v[140:143], v[210:213], v[12:15]
	v_mfma_f32_16x16x32_bf16 v[20:23], v[132:135], v[210:213], v[20:23]
	v_mfma_f32_16x16x32_bf16 v[20:23], v[128:131], v[206:209], v[20:23]
	s_setprio 0
	s_setprio 1
	v_mfma_f32_16x16x32_bf16 v[52:55], v[160:163], v[182:185], v[52:55]
	v_mfma_f32_16x16x32_bf16 v[52:55], v[170:173], v[186:189], v[52:55]
	v_mfma_f32_16x16x32_bf16 v[44:47], v[178:181], v[186:189], v[44:47]
	v_mfma_f32_16x16x32_bf16 v[44:47], v[174:177], v[182:185], v[44:47]
	v_mfma_f32_16x16x32_bf16 v[32:35], v[174:177], v[190:193], v[32:35]
	v_mfma_f32_16x16x32_bf16 v[32:35], v[178:181], v[194:197], v[32:35]
	v_mfma_f32_16x16x32_bf16 v[36:39], v[170:173], v[194:197], v[36:39]
	v_mfma_f32_16x16x32_bf16 v[36:39], v[160:163], v[190:193], v[36:39]
	v_mfma_f32_16x16x32_bf16 v[16:19], v[160:163], v[198:201], v[16:19]
	v_mfma_f32_16x16x32_bf16 v[16:19], v[170:173], v[202:205], v[16:19]
	v_mfma_f32_16x16x32_bf16 v[8:11], v[178:181], v[202:205], v[8:11]
	v_mfma_f32_16x16x32_bf16 v[8:11], v[174:177], v[198:201], v[8:11]
	v_mfma_f32_16x16x32_bf16 v[0:3], v[174:177], v[206:209], v[0:3]
	v_mfma_f32_16x16x32_bf16 v[0:3], v[178:181], v[210:213], v[0:3]
	v_mfma_f32_16x16x32_bf16 v[4:7], v[170:173], v[210:213], v[4:7]
	v_mfma_f32_16x16x32_bf16 v[4:7], v[160:163], v[206:209], v[4:7]
	s_setprio 0
	s_barrier
	s_add_i32 s58, 0, 0x18000
	s_add_i32 s59, 0, 0x1c000
	v_add_u32_e32 v140, s58, v165
	v_add_u32_e32 v178, s59, v165
	ds_read_b128 v[128:131], v140
	ds_read_b128 v[132:135], v140 offset:1024
	ds_read_b128 v[136:139], v140 offset:2048
	ds_read_b128 v[140:143], v140 offset:3072
	ds_read_b128 v[160:163], v178
	ds_read_b128 v[170:173], v178 offset:1024
	ds_read_b128 v[174:177], v178 offset:2048
	ds_read_b128 v[178:181], v178 offset:3072
	s_add_u32 s14, s20, 0x2b0000
	s_addc_u32 s15, s21, 0
	s_mov_b32 m0, s27
	v_lshl_add_u64 v[222:223], s[14:15], 0, v[144:145]
	ds_read_b128 v[182:185], v169 offset:32768
	ds_read_b128 v[186:189], v169 offset:33792
	ds_read_b128 v[190:193], v169 offset:34816
	ds_read_b128 v[194:197], v169 offset:35840
	ds_read_b128 v[198:201], v169 offset:36864
	ds_read_b128 v[202:205], v169 offset:37888
	ds_read_b128 v[206:209], v169 offset:38912
	ds_read_b128 v[210:213], v169 offset:39936
	global_load_lds_dwordx4 v[222:223], off
	v_lshl_add_u64 v[222:223], s[14:15], 0, v[148:149]
	s_mov_b32 m0, s28
	s_nop 0
	global_load_lds_dwordx4 v[222:223], off
	s_waitcnt vmcnt(8)
	s_waitcnt lgkmcnt(0)
	s_barrier
	s_setprio 1
	s_waitcnt lgkmcnt(0)
	v_mfma_f32_16x16x32_bf16 v[124:127], v[128:131], v[182:185], v[124:127]
	v_mfma_f32_16x16x32_bf16 v[124:127], v[132:135], v[186:189], v[124:127]
	v_mfma_f32_16x16x32_bf16 v[120:123], v[140:143], v[186:189], v[120:123]
	v_mfma_f32_16x16x32_bf16 v[120:123], v[136:139], v[182:185], v[120:123]
	v_mfma_f32_16x16x32_bf16 v[108:111], v[136:139], v[190:193], v[108:111]
	v_mfma_f32_16x16x32_bf16 v[108:111], v[140:143], v[194:197], v[108:111]
	v_mfma_f32_16x16x32_bf16 v[116:119], v[132:135], v[194:197], v[116:119]
	v_mfma_f32_16x16x32_bf16 v[116:119], v[128:131], v[190:193], v[116:119]
	v_mfma_f32_16x16x32_bf16 v[92:95], v[128:131], v[198:201], v[92:95]
	v_mfma_f32_16x16x32_bf16 v[92:95], v[132:135], v[202:205], v[92:95]
	v_mfma_f32_16x16x32_bf16 v[88:91], v[140:143], v[202:205], v[88:91]
	v_mfma_f32_16x16x32_bf16 v[88:91], v[136:139], v[198:201], v[88:91]
	v_mfma_f32_16x16x32_bf16 v[72:75], v[136:139], v[206:209], v[72:75]
	v_mfma_f32_16x16x32_bf16 v[72:75], v[140:143], v[210:213], v[72:75]
	v_mfma_f32_16x16x32_bf16 v[80:83], v[132:135], v[210:213], v[80:83]
	v_mfma_f32_16x16x32_bf16 v[80:83], v[128:131], v[206:209], v[80:83]
	s_setprio 0
	s_setprio 1
	v_mfma_f32_16x16x32_bf16 v[112:115], v[160:163], v[182:185], v[112:115]
	v_mfma_f32_16x16x32_bf16 v[112:115], v[170:173], v[186:189], v[112:115]
	v_mfma_f32_16x16x32_bf16 v[104:107], v[178:181], v[186:189], v[104:107]
	v_mfma_f32_16x16x32_bf16 v[104:107], v[174:177], v[182:185], v[104:107]
	v_mfma_f32_16x16x32_bf16 v[96:99], v[174:177], v[190:193], v[96:99]
	v_mfma_f32_16x16x32_bf16 v[96:99], v[178:181], v[194:197], v[96:99]
	v_mfma_f32_16x16x32_bf16 v[100:103], v[170:173], v[194:197], v[100:103]
	v_mfma_f32_16x16x32_bf16 v[100:103], v[160:163], v[190:193], v[100:103]
	v_mfma_f32_16x16x32_bf16 v[84:87], v[160:163], v[198:201], v[84:87]
	v_mfma_f32_16x16x32_bf16 v[84:87], v[170:173], v[202:205], v[84:87]
	v_mfma_f32_16x16x32_bf16 v[76:79], v[178:181], v[202:205], v[76:79]
	v_mfma_f32_16x16x32_bf16 v[76:79], v[174:177], v[198:201], v[76:79]
	v_mfma_f32_16x16x32_bf16 v[64:67], v[174:177], v[206:209], v[64:67]
	v_mfma_f32_16x16x32_bf16 v[64:67], v[178:181], v[210:213], v[64:67]
	v_mfma_f32_16x16x32_bf16 v[68:71], v[170:173], v[210:213], v[68:71]
	v_mfma_f32_16x16x32_bf16 v[68:71], v[160:163], v[206:209], v[68:71]
	s_setprio 0
	s_barrier
; #define PG8_STAGE(bufoff, gbase, voff) do { _Pragma("unroll") for (int _i = 0; _i < 2; ++_i) \
;         __builtin_amdgcn_global_load_lds((const unsigned*)((const char*)(gbase) + (voff)[_i]), (PG8_LAS unsigned*)(lds + (bufoff) + ldsw + _i * 8192), 16, 0, 0); } while (0)
; #define PG8_LDA(dst, b, h) do { _Pragma("unroll") for (int m = 0; m < 4; ++m) _Pragma("unroll") for (int k = 0; k < 2; ++k) dst[m][k] = *(const PG8_LAS bf16x8*)(lds + PG8_SA(b, h) + aoff + m * 2048 + k * 1024); } while (0)
; #define PG8_MMA(ai, bj, At, Bt) do { __builtin_amdgcn_s_setprio(1); _Pragma("unroll") for (int m = 0; m < 4; ++m) _Pragma("unroll") for (int n = 0; n < 2; ++n) _Pragma("unroll") for (int k = 0; k < 2; ++k) \
;         acc[ai][bj][m][n] = __builtin_amdgcn_mfma_f32_16x16x32_bf16(Bt[n][k], At[m][k], acc[ai][bj][m][n], 0, 0, 0); __builtin_amdgcn_s_setprio(0); } while (0)
; #define PG8_WAIT_V(n) asm volatile("s_waitcnt vmcnt(" #n ")" ::: "memory")
; #define PG8_WAIT_L(n) asm volatile("s_waitcnt lgkmcnt(" #n ")" ::: "memory")
; #define PG8_BAR __builtin_amdgcn_s_barrier()
; #define PG8_SCHED __builtin_amdgcn_sched_barrier(0)
; template <class Epi, class Sched, bool ALIGN_EPI = false, bool SP2 = false>
; __device__ __forceinline__ void gemm_phase(PG8_LAS unsigned char* lds, const Gemm g, const Sched& S, const Epi& E) {
;     ...
;             PG8_LDA(At, 1, 1); PG8_STAGE(PG8_SB(1, 0), b3, voffB); PG8_STAGE(PG8_SB(1, 1), b3 + hstepB, voffB); PG8_STAGE(PG8_SA(1, 0), a3, voffA);
;             PG8_WAIT_V(8); PG8_WAIT_L(0); PG8_BAR; PG8_MMA(1, 0, At, B0); PG8_MMA(1, 1, At, B1); PG8_BAR; PG8_SCHED;
	s_add_i32 s14, s58, s24
	v_lshl_add_u64 v[214:215], v[214:215], 0, s[8:9]
	s_mov_b32 m0, s14
	ds_read_b128 v[182:185], v169 offset:49152
	ds_read_b128 v[186:189], v169 offset:50176
	ds_read_b128 v[190:193], v169 offset:51200
	ds_read_b128 v[194:197], v169 offset:52224
	ds_read_b128 v[198:201], v169 offset:53248
	ds_read_b128 v[202:205], v169 offset:54272
	ds_read_b128 v[206:209], v169 offset:55296
	ds_read_b128 v[210:213], v169 offset:56320
	global_load_lds_dwordx4 v[214:215], off
	s_add_i32 m0, s14, 0x2000
	s_add_u32 s14, s18, 0x2b0080
	v_lshl_add_u64 v[214:215], v[216:217], 0, s[8:9]
	s_addc_u32 s15, s19, 0
	s_add_i32 s18, s59, s24
	global_load_lds_dwordx4 v[214:215], off
	v_lshl_add_u64 v[214:215], s[14:15], 0, v[146:147]
	s_mov_b32 m0, s18
	s_nop 0
	global_load_lds_dwordx4 v[214:215], off
	v_lshl_add_u64 v[214:215], s[14:15], 0, v[150:151]
	s_add_i32 m0, s18, 0x2000
	s_nop 0
	global_load_lds_dwordx4 v[214:215], off
	v_lshl_add_u64 v[214:215], v[218:219], 0, s[8:9]
	s_mov_b32 m0, s33
	s_nop 0
	global_load_lds_dwordx4 v[214:215], off
	v_lshl_add_u64 v[214:215], v[220:221], 0, s[8:9]
	s_mov_b32 m0, s34
	s_nop 0
	global_load_lds_dwordx4 v[214:215], off
	s_waitcnt vmcnt(8)
	s_waitcnt lgkmcnt(0)
	s_barrier
	s_setprio 1
	s_waitcnt lgkmcnt(0)
	v_mfma_f32_16x16x32_bf16 v[60:63], v[128:131], v[182:185], v[60:63]
	v_mfma_f32_16x16x32_bf16 v[60:63], v[132:135], v[186:189], v[60:63]
	v_mfma_f32_16x16x32_bf16 v[56:59], v[140:143], v[186:189], v[56:59]
	v_mfma_f32_16x16x32_bf16 v[56:59], v[136:139], v[182:185], v[56:59]
	v_mfma_f32_16x16x32_bf16 v[40:43], v[136:139], v[190:193], v[40:43]
	v_mfma_f32_16x16x32_bf16 v[40:43], v[140:143], v[194:197], v[40:43]
	v_mfma_f32_16x16x32_bf16 v[48:51], v[132:135], v[194:197], v[48:51]
	v_mfma_f32_16x16x32_bf16 v[48:51], v[128:131], v[190:193], v[48:51]
	v_mfma_f32_16x16x32_bf16 v[28:31], v[128:131], v[198:201], v[28:31]
	v_mfma_f32_16x16x32_bf16 v[28:31], v[132:135], v[202:205], v[28:31]
	v_mfma_f32_16x16x32_bf16 v[24:27], v[140:143], v[202:205], v[24:27]
	v_mfma_f32_16x16x32_bf16 v[24:27], v[136:139], v[198:201], v[24:27]
	v_mfma_f32_16x16x32_bf16 v[12:15], v[136:139], v[206:209], v[12:15]
	v_mfma_f32_16x16x32_bf16 v[12:15], v[140:143], v[210:213], v[12:15]
	v_mfma_f32_16x16x32_bf16 v[20:23], v[132:135], v[210:213], v[20:23]
	v_mfma_f32_16x16x32_bf16 v[20:23], v[128:131], v[206:209], v[20:23]
	s_setprio 0
	s_setprio 1
	v_mfma_f32_16x16x32_bf16 v[52:55], v[160:163], v[182:185], v[52:55]
	v_mfma_f32_16x16x32_bf16 v[52:55], v[170:173], v[186:189], v[52:55]
	v_mfma_f32_16x16x32_bf16 v[44:47], v[178:181], v[186:189], v[44:47]
	v_mfma_f32_16x16x32_bf16 v[44:47], v[174:177], v[182:185], v[44:47]
	v_mfma_f32_16x16x32_bf16 v[32:35], v[174:177], v[190:193], v[32:35]
	v_mfma_f32_16x16x32_bf16 v[32:35], v[178:181], v[194:197], v[32:35]
	v_mfma_f32_16x16x32_bf16 v[36:39], v[170:173], v[194:197], v[36:39]
	v_mfma_f32_16x16x32_bf16 v[36:39], v[160:163], v[190:193], v[36:39]
	v_mfma_f32_16x16x32_bf16 v[16:19], v[160:163], v[198:201], v[16:19]
	v_mfma_f32_16x16x32_bf16 v[16:19], v[170:173], v[202:205], v[16:19]
	v_mfma_f32_16x16x32_bf16 v[8:11], v[178:181], v[202:205], v[8:11]
	v_mfma_f32_16x16x32_bf16 v[8:11], v[174:177], v[198:201], v[8:11]
	v_mfma_f32_16x16x32_bf16 v[0:3], v[174:177], v[206:209], v[0:3]
	v_mfma_f32_16x16x32_bf16 v[0:3], v[178:181], v[210:213], v[0:3]
	v_mfma_f32_16x16x32_bf16 v[4:7], v[170:173], v[210:213], v[4:7]
	v_mfma_f32_16x16x32_bf16 v[4:7], v[160:163], v[206:209], v[4:7]
	s_setprio 0
	s_barrier
	s_add_i32 s57, s57, 2
	s_add_u32 s55, s55, 0x100
	s_addc_u32 s56, s56, 0
	s_cmpk_gt_u32 s57, 0xa9
	s_mov_b64 s[14:15], s[16:17]
	s_cbranch_scc0 .LBB0_2165
	s_and_b64 vcc, exec, s[10:11]
	s_cbranch_vccz .LBB0_2168
	s_barrier
